# GEMM k-loops (E1, O1, Q-up, KV-up, O4, E3): the first k-step's LDS fragment reads (and their address adds) moved from behind hipcc's ~25-instruction scalar tile-index block to the barrier release, so
# speedup vs baseline: 1.0025x; 1.0025x over previous
; __device__ __forceinline__ void tile_of(int pos, int ntn, int& mt, int& nt) {
;   const int full = 64 * ntn;
;   if (pos < full) { const int panel = pos / (8 * ntn); const int rem = pos - panel * 8 * ntn; nt = rem >> 3; mt = panel * 8 + (rem & 7); }
;   else { mt = 64; nt = pos - full; }
;     ...
;     auto compute = [&](int buf) {
;       const unsigned char* Ab = As + buf * ASTG + (wn * 64 + lr) * 128;
;       const unsigned char* Ax = Ax0 + buf * 128;
;       const unsigned char* Bb = Bs + buf * 16384 + (wm * 64 + lr) * 128;
; #pragma unroll
;       for (int ks = 0; ks < 2; ++ks) {
;         if (TI == 5 && ks == 1) __builtin_amdgcn_sched_barrier(0);
;         const int sw = ((ks * 4 + lq) ^ (lr & 7)) << 4;
;         bf16x8 wf[4], xf[TI];
; #pragma unroll
;         for (int i = 0; i < 4; ++i) {
;           wf[i] = *(const bf16x8*)(Bb + i * 2048 + sw);
;           xf[i] = *(const bf16x8*)(Ab + i * 2048 + sw);
;         }
.LBB0_589:
	v_add_u32_e32 v125, v143, v144
	ds_read_b128 v[30:33], v125 offset:32768
	v_add_u32_e32 v130, v142, v144
	ds_read_b128 v[34:37], v130
	ds_read_b128 v[38:41], v125 offset:34816
	ds_read_b128 v[42:45], v130 offset:2048
	s_min_i32 s11, s7, s31
	s_cmpk_gt_i32 s11, 0x3bf
	s_mov_b64 s[4:5], -1
	s_cbranch_scc0 .LBB0_591
	s_add_i32 s10, s11, 0xfffffc40
	s_mov_b64 s[4:5], 0

; #define MFMA16(a, b, c) __builtin_amdgcn_mfma_f32_16x16x32_bf16((a), (b), (c), 0, 0, 0)
;     ...
;     auto issue = [&](u32x4 (&ra)[4], u32x4 (&rb)[2], u32x4& rx) {
;       const int idc = l_id < last_id ? l_id : last_id;
;       int mt, nt; if (TMAP == 1) rem_tile(idc, mt, nt); else tile_of(idc, ntn, mt, nt);
;       const bf16_t* A = (l_kt < ktsplit) ? A0 : A1;
;       const int kk = (l_kt < ktsplit) ? l_kt : l_kt - ktsplit;
;       const int arow = mt * 2 * BMH + hh * BMH + srow;
;       const bf16_t* akb = A + kk * kstride + (tid & 7) * 8;
;       const bf16_t* wp = W + (size_t)(nt * 128 + wrow) * K + l_kt * 64 + (tid5 & 7) * 8;
; #pragma unroll
;       for (int i = 0; i < 4; ++i) {
;         int r = arow + 32 * i; r = r < M_ ? r : M_ - 1;
;         ra[i] = *(const u32x4*)(akb + (size_t)r * lda);
;       }
; #pragma unroll
;       for (int i = 0; i < 2; ++i) rb[i] = *(const u32x4*)(wp + (size_t)i * 64 * K);
;       if (TI == 5) rx = *(const u32x4*)(akb + (size_t)(arow - srow + 128) * lda);
;       if (++l_kt == nk) { l_kt = 0; l_id += G; }
;     };
;     ...
;     auto compute = [&](int buf) {
;       const unsigned char* Ab = As + buf * ASTG + (wn * 64 + lr) * 128;
;       const unsigned char* Ax = Ax0 + buf * 128;
;       const unsigned char* Bb = Bs + buf * 16384 + (wm * 64 + lr) * 128;
; #pragma unroll
;       for (int ks = 0; ks < 2; ++ks) {
;         if (TI == 5 && ks == 1) __builtin_amdgcn_sched_barrier(0);
;         const int sw = ((ks * 4 + lq) ^ (lr & 7)) << 4;
;         bf16x8 wf[4], xf[TI];
; #pragma unroll
;         for (int i = 0; i < 4; ++i) {
;           wf[i] = *(const bf16x8*)(Bb + i * 2048 + sw);
;           xf[i] = *(const bf16x8*)(Ab + i * 2048 + sw);
;         }
;         if (TI == 5) xf[TI - 1] = *(const bf16x8*)(Ax + ((ks * 4 + lq) << 4));
; #pragma unroll
;         for (int ni = 0; ni < 4; ++ni)
; #pragma unroll
;           for (int ti = 0; ti < 4; ++ti) acc[ni][ti] = MFMA16(wf[ni], xf[ti], acc[ni][ti]);
;         if (TI == 5) {
;           if (wn == 0) { acc[0][TI - 1] = MFMA16(wf[0], xf[TI - 1], acc[0][TI - 1]); acc[1][TI - 1] = MFMA16(wf[1], xf[TI - 1], acc[1][TI - 1]); }
;           else { acc[2][TI - 1] = MFMA16(wf[2], xf[TI - 1], acc[2][TI - 1]); acc[3][TI - 1] = MFMA16(wf[3], xf[TI - 1], acc[3][TI - 1]); }
;         }
;       }
;     };
.LBB0_593:
	s_cmp_lt_i32 s6, 2.0
	s_waitcnt lgkmcnt(1)
	v_mfma_f32_16x16x32_bf16 v[94:97], v[38:41], v[34:37], v[94:97]
	s_cselect_b32 s11, s43, 0
	s_cselect_b32 s12, s42, 0
	v_add_u32_e32 v117, s4, v139
	v_mfma_f32_16x16x32_bf16 v[50:53], v[30:33], v[34:37], v[110:113]
	s_lshl_b32 s4, s6, 6
	s_ashr_i32 s5, s4, 31
	s_lshl_b64 s[4:5], s[4:5], 1
	s_waitcnt lgkmcnt(0)
	v_mfma_f32_16x16x32_bf16 v[54:57], v[30:33], v[42:45], v[106:109]
	s_nop 2
	ds_read_b128 v[106:109], v130 offset:4096
	ds_read_b128 v[110:113], v130 offset:6144
	v_add_u32_e32 v13, v143, v145
	s_add_u32 s12, s12, s4
	s_waitcnt lgkmcnt(1)
	v_mfma_f32_16x16x32_bf16 v[102:105], v[30:33], v[106:109], v[102:105]
	s_addc_u32 s13, s11, s5
	v_mov_b32_e32 v115, v12
	v_add_u32_e32 v131, v142, v145
	s_waitcnt lgkmcnt(0)
	v_mfma_f32_16x16x32_bf16 v[30:33], v[30:33], v[110:113], v[98:101]
	s_mov_b32 s2, 0x20000
	s_mov_b32 s3, 0x30000
	s_add_i32 s35, s9, 1
	v_mfma_f32_16x16x32_bf16 v[90:93], v[38:41], v[42:45], v[90:93]
	ds_read_b128 v[98:101], v125 offset:36864
	s_cmp_lg_u32 s35, 16
	v_mfma_f32_16x16x32_bf16 v[86:89], v[38:41], v[106:109], v[86:89]
	v_mfma_f32_16x16x32_bf16 v[82:85], v[38:41], v[110:113], v[82:85]
	ds_read_b128 v[38:41], v125 offset:38912
	s_waitcnt lgkmcnt(0)
	v_mfma_f32_16x16x32_bf16 v[158:161], v[38:41], v[34:37], v[62:65]
	s_nop 2
	ds_read_b128 v[62:65], v13 offset:32768
	v_mfma_f32_16x16x32_bf16 v[132:135], v[98:101], v[34:37], v[78:81]
	v_min_i32_e32 v34, 0x405f, v117
	v_ashrrev_i32_e32 v35, 31, v34
	v_lshlrev_b64 v[34:35], 11, v[34:35]
	v_mfma_f32_16x16x32_bf16 v[150:153], v[98:101], v[42:45], v[74:77]
	s_nop 2
	v_lshl_add_u64 v[74:75], s[12:13], 0, v[114:115]
	v_mfma_f32_16x16x32_bf16 v[154:157], v[98:101], v[106:109], v[70:73]
	v_lshl_add_u64 v[34:35], v[74:75], 0, v[34:35]
	v_add_co_u32_e32 v34, vcc, s82, v34
	s_nop 0
	v_min_i32_e32 v70, 0x407f, v117
	v_ashrrev_i32_e32 v71, 31, v70
	v_mfma_f32_16x16x32_bf16 v[98:101], v[98:101], v[110:113], v[66:69]
	v_addc_co_u32_e32 v35, vcc, 0, v35, vcc
	v_lshl_add_u32 v76, s10, 7, v138
	s_nop 0
	v_lshlrev_b64 v[66:67], 11, v[70:71]
	v_lshl_add_u64 v[66:67], v[74:75], 0, v[66:67]
	v_mfma_f32_16x16x32_bf16 v[168:171], v[38:41], v[42:45], v[58:61]
	v_ashrrev_i32_e32 v77, 31, v76
	v_mfma_f32_16x16x32_bf16 v[176:179], v[38:41], v[106:109], v[46:49]
	ds_read_b128 v[106:109], v131
	global_load_dwordx4 v[42:45], v[66:67], off
	s_nop 0
	global_load_dwordx4 v[34:37], v[34:35], off
	ds_read_b128 v[78:81], v13 offset:34816
	ds_read_b128 v[202:205], v131 offset:2048
	ds_read_b128 v[206:209], v131 offset:4096
	ds_read_b128 v[210:213], v131 offset:6144
	v_mfma_f32_16x16x32_bf16 v[180:183], v[38:41], v[110:113], v[26:29]
	v_min_i32_e32 v38, 0x403f, v117
	v_ashrrev_i32_e32 v39, 31, v38
	v_lshlrev_b64 v[38:39], 11, v[38:39]
	v_min_i32_e32 v40, 0x401f, v117
	v_lshl_add_u64 v[38:39], v[74:75], 0, v[38:39]
	v_ashrrev_i32_e32 v41, 31, v40
	s_waitcnt lgkmcnt(4)
	v_mfma_f32_16x16x32_bf16 v[26:29], v[62:65], v[106:109], v[50:53]
	v_add_co_u32_e32 v38, vcc, s2, v38
	v_mov_b32_e32 v117, v12
	s_waitcnt lgkmcnt(2)
	v_mfma_f32_16x16x32_bf16 v[46:49], v[62:65], v[202:205], v[54:57]
	v_lshlrev_b64 v[50:51], 11, v[76:77]
	v_addc_co_u32_e32 v39, vcc, 0, v39, vcc
	s_waitcnt lgkmcnt(1)
	v_mfma_f32_16x16x32_bf16 v[58:61], v[62:65], v[206:209], v[102:105]
	v_lshl_add_u64 v[50:51], s[44:45], 0, v[50:51]
	v_lshl_add_u64 v[50:51], v[50:51], 0, s[4:5]
	v_lshl_add_u64 v[50:51], v[50:51], 0, v[116:117]
	s_waitcnt lgkmcnt(0)
	v_mfma_f32_16x16x32_bf16 v[62:65], v[62:65], v[210:213], v[30:33]
	s_waitcnt vmcnt(7)
	v_and_b32_e32 v103, 0xffff0000, v4
	s_waitcnt vmcnt(6)
	v_and_b32_e32 v102, 0xffff0000, v0
	v_pk_mul_f32 v[136:137], v[102:103], v[102:103]
	v_lshlrev_b64 v[30:31], 11, v[40:41]
	v_lshl_add_u64 v[30:31], v[74:75], 0, v[30:31]
	v_add_co_u32_e32 v30, vcc, s3, v30
	v_mfma_f32_16x16x32_bf16 v[66:69], v[78:81], v[106:109], v[94:97]
	s_nop 0
	v_addc_co_u32_e32 v31, vcc, 0, v31, vcc
	v_add_co_u32_e32 v52, vcc, s2, v50
	global_load_dwordx4 v[38:41], v[38:39], off
	s_nop 0
	global_load_dwordx4 v[30:33], v[30:31], off
	v_addc_co_u32_e32 v53, vcc, 0, v51, vcc
	ds_read_b128 v[94:97], v13 offset:36864
	ds_read_b128 v[214:217], v13 offset:38912
	global_load_dwordx4 v[54:57], v[50:51], off
	s_nop 0
	global_load_dwordx4 v[50:53], v[52:53], off
	v_mfma_f32_16x16x32_bf16 v[70:73], v[78:81], v[202:205], v[90:93]
	ds_write_b128 v141, v[4:7] offset:16384
	ds_write_b128 v141, v[0:3] offset:20480
	s_waitcnt vmcnt(9)
;     ...
;     auto store = [&](const u32x4 (&ra)[4], const u32x4 (&rb)[2], const u32x4& rx, int buf) {
; #pragma unroll
;       for (int i = 0; i < 4; ++i) {
;         if (RS) ss[i] += sumsq8(__builtin_bit_cast(bf16x8, ra[i]));
;         *(u32x4*)(As + buf * ASTG + i * 4096 + soff) = ra[i];
;       }
; #pragma unroll
;       for (int i = 0; i < 2; ++i) *(u32x4*)(Bs + buf * 16384 + i * 8192 + woff) = rb[i];
;       if (TI == 5) {
;         if (RS) ss[4] += sumsq8(__builtin_bit_cast(bf16x8, rx));
;         if (srow == 0) *(u32x4*)(Ax0 + buf * 128 + ((tid & 7) << 4)) = rx;
;       }
;       if (RS) {
;         if (++st_kt == nk) {
;           st_kt = 0;
; #pragma unroll
;           for (int i = 0; i < TI; ++i) {
;             float t = ss[i];
;             t += __shfl_xor(t, 1); t += __shfl_xor(t, 2); t += __shfl_xor(t, 4);
;             if ((tid & 7) == 0 && i < 4) rsl[srow + 32 * i] = rsqrtf(t * invK + EPS_);
;             ss[i] = 0.f;
;           }
;         }
;       }
;     };
	ds_write_b128 v141, v[14:17] offset:24576
	v_mfma_f32_16x16x32_bf16 v[74:77], v[78:81], v[206:209], v[86:89]
	s_waitcnt vmcnt(8)
	ds_write_b128 v141, v[8:11] offset:28672
	s_waitcnt vmcnt(7)
	ds_write_b128 v140, v[22:25] offset:49152
	s_waitcnt vmcnt(6)
	ds_write_b128 v140, v[18:21] offset:57344
	v_mfma_f32_16x16x32_bf16 v[78:81], v[78:81], v[210:213], v[82:85]
	s_waitcnt lgkmcnt(7)
	v_mfma_f32_16x16x32_bf16 v[82:85], v[94:97], v[106:109], v[132:135]
	s_nop 2
	v_lshlrev_b32_e32 v135, 16, v4
	v_lshlrev_b32_e32 v134, 16, v0
	v_and_b32_e32 v133, 0xffff0000, v5
	v_mfma_f32_16x16x32_bf16 v[86:89], v[94:97], v[202:205], v[150:153]
	v_lshlrev_b32_e32 v5, 16, v5
	v_lshlrev_b32_e32 v4, 16, v1
	v_and_b32_e32 v132, 0xffff0000, v1
	v_mfma_f32_16x16x32_bf16 v[90:93], v[94:97], v[206:209], v[154:157]
	v_and_b32_e32 v1, 0xffff0000, v15
	v_and_b32_e32 v0, 0xffff0000, v9
	v_mfma_f32_16x16x32_bf16 v[110:113], v[94:97], v[210:213], v[98:101]
	v_fma_f32 v94, v134, v134, v136
	v_fma_f32 v95, v135, v135, v137
	v_pk_fma_f32 v[4:5], v[4:5], v[4:5], v[94:95]
	v_lshlrev_b32_e32 v95, 16, v6
	v_pk_fma_f32 v[4:5], v[132:133], v[132:133], v[4:5]
	v_lshlrev_b32_e32 v94, 16, v2
	v_pk_fma_f32 v[4:5], v[94:95], v[94:95], v[4:5]
	v_and_b32_e32 v99, 0xffff0000, v6
	v_and_b32_e32 v98, 0xffff0000, v2
	v_pk_fma_f32 v[4:5], v[98:99], v[98:99], v[4:5]
	v_lshlrev_b32_e32 v133, 16, v7
	v_lshlrev_b32_e32 v132, 16, v3
	v_pk_fma_f32 v[4:5], v[132:133], v[132:133], v[4:5]
	v_and_b32_e32 v7, 0xffff0000, v7
	v_and_b32_e32 v6, 0xffff0000, v3
	v_pk_fma_f32 v[4:5], v[6:7], v[6:7], v[4:5]
	v_lshlrev_b32_e32 v3, 16, v14
	v_pk_add_f32 v[128:129], v[128:129], v[4:5]
	v_and_b32_e32 v5, 0xffff0000, v14
	v_and_b32_e32 v4, 0xffff0000, v8
	v_lshlrev_b32_e32 v2, 16, v8
	v_pk_mul_f32 v[4:5], v[4:5], v[4:5]
	v_lshlrev_b32_e32 v7, 16, v15
	v_lshlrev_b32_e32 v6, 16, v9
	v_pk_fma_f32 v[2:3], v[2:3], v[2:3], v[4:5]
	s_waitcnt lgkmcnt(6)
	v_mfma_f32_16x16x32_bf16 v[102:105], v[214:217], v[106:109], v[158:161]
	v_fma_f32 v2, v6, v6, v2
	v_fma_f32 v3, v7, v7, v3
	v_pk_fma_f32 v[0:1], v[0:1], v[0:1], v[2:3]
	v_lshlrev_b32_e32 v3, 16, v16
	v_lshlrev_b32_e32 v2, 16, v10
	v_pk_fma_f32 v[0:1], v[2:3], v[2:3], v[0:1]
	v_and_b32_e32 v3, 0xffff0000, v16
	v_and_b32_e32 v2, 0xffff0000, v10
	v_mfma_f32_16x16x32_bf16 v[106:109], v[214:217], v[202:205], v[168:171]
	v_fma_f32 v0, v2, v2, v0
	v_fma_f32 v1, v3, v3, v1
	v_lshlrev_b32_e32 v3, 16, v17
	v_lshlrev_b32_e32 v2, 16, v11
	v_mfma_f32_16x16x32_bf16 v[94:97], v[214:217], v[206:209], v[176:179]
	v_fma_f32 v0, v2, v2, v0
	v_fma_f32 v1, v3, v3, v1
	v_and_b32_e32 v3, 0xffff0000, v17
	v_and_b32_e32 v2, 0xffff0000, v11
	v_mfma_f32_16x16x32_bf16 v[98:101], v[214:217], v[210:213], v[180:183]
	v_fma_f32 v0, v2, v2, v0
	v_fma_f32 v1, v3, v3, v1
	v_pk_add_f32 v[126:127], v[126:127], v[0:1]
	s_cbranch_scc1 .LBB0_603
	v_and_b32_e32 v1, 64, v191
	v_xor_b32_e32 v0, 1, v191
	v_add_u32_e32 v2, 64, v1
	v_cmp_lt_i32_e32 vcc, v0, v2
	v_xor_b32_e32 v1, 2, v191
	v_xor_b32_e32 v5, 4, v191
	v_cndmask_b32_e32 v0, v191, v0, vcc
	v_lshlrev_b32_e32 v0, 2, v0
	ds_bpermute_b32 v3, v0, v129
	v_cmp_lt_i32_e32 vcc, v1, v2
	s_waitcnt lgkmcnt(0)
	v_add_f32_e32 v3, v129, v3
	v_cndmask_b32_e32 v1, v191, v1, vcc
	v_lshlrev_b32_e32 v1, 2, v1
	ds_bpermute_b32 v4, v1, v3
	v_cmp_lt_i32_e32 vcc, v5, v2
	s_waitcnt lgkmcnt(0)
	v_add_f32_e32 v3, v3, v4
	v_cndmask_b32_e32 v2, v191, v5, vcc
	v_lshlrev_b32_e32 v2, 2, v2
	ds_bpermute_b32 v4, v2, v3
	s_and_saveexec_b64 s[4:5], s[38:39]
	s_cbranch_execz .LBB0_596
	s_waitcnt lgkmcnt(0)
	v_add_f32_e32 v3, v3, v4
	v_fmamk_f32 v3, v3, 0x3a800000, v187
	v_mul_f32_e32 v4, 0x4b800000, v3
	v_cmp_gt_f32_e32 vcc, s33, v3
	s_nop 1
	v_cndmask_b32_e32 v3, v3, v4, vcc
	v_rsq_f32_e32 v3, v3
	s_nop 0
	v_mul_f32_e32 v4, 0x45800000, v3
	v_cndmask_b32_e32 v3, v3, v4, vcc
	ds_write_b32 v146, v3

; __device__ __forceinline__ void rem_tile(int pos, int& mt, int& nt) { if (pos < 65) { mt = pos; nt = 40; } else { mt = 64; nt = pos - 65; } }
;     ...
;     auto issue = [&](u32x4 (&ra)[4], u32x4 (&rb)[2], u32x4& rx) {
;       const int idc = l_id < last_id ? l_id : last_id;
;       int mt, nt; if (TMAP == 1) rem_tile(idc, mt, nt); else tile_of(idc, ntn, mt, nt);
;       const bf16_t* A = (l_kt < ktsplit) ? A0 : A1;
;       const int kk = (l_kt < ktsplit) ? l_kt : l_kt - ktsplit;
;       const int arow = mt * 2 * BMH + hh * BMH + srow;
;     ...
; #pragma unroll 1
;     for (int s = 0; s < S; s += 2) {
;       issue(ra0, rb0, rx0);
;       compute(0);
;       store(ra1, rb1, rx1, 1);
;       __syncthreads();
;       issue(ra1, rb1, rx1);
.LBB0_603:
	s_add_i32 s10, s6, 1
	s_cmp_eq_u32 s10, 16
	s_cselect_b64 s[4:5], -1, 0
	s_and_b64 s[12:13], s[4:5], exec
	s_load_dwordx2 s[12:13], s[0:1], 0x110
	s_waitcnt lgkmcnt(0)
	s_barrier
	ds_read_b128 v[0:3], v125 offset:49152
	ds_read_b128 v[4:7], v130 offset:16384
	ds_read_b128 v[8:11], v125 offset:51200
	ds_read_b128 v[14:17], v130 offset:18432
	s_cselect_b32 s34, s12, 0
	s_add_i32 s34, s34, s7
	s_min_i32 s11, s34, s31
	s_cmpk_gt_i32 s11, 0x3bf
	s_mov_b64 s[6:7], -1
	s_cbranch_scc0 .LBB0_605
	s_add_i32 s9, s11, 0xfffffc40
	s_mov_b64 s[6:7], 0

; #define MFMA16(a, b, c) __builtin_amdgcn_mfma_f32_16x16x32_bf16((a), (b), (c), 0, 0, 0)
;     ...
;     auto issue = [&](u32x4 (&ra)[4], u32x4 (&rb)[2], u32x4& rx) {
;       const int idc = l_id < last_id ? l_id : last_id;
;       int mt, nt; if (TMAP == 1) rem_tile(idc, mt, nt); else tile_of(idc, ntn, mt, nt);
;       const bf16_t* A = (l_kt < ktsplit) ? A0 : A1;
;       const int kk = (l_kt < ktsplit) ? l_kt : l_kt - ktsplit;
;       const int arow = mt * 2 * BMH + hh * BMH + srow;
;       const bf16_t* akb = A + kk * kstride + (tid & 7) * 8;
;       const bf16_t* wp = W + (size_t)(nt * 128 + wrow) * K + l_kt * 64 + (tid5 & 7) * 8;
; #pragma unroll
;       for (int i = 0; i < 4; ++i) {
;         int r = arow + 32 * i; r = r < M_ ? r : M_ - 1;
;         ra[i] = *(const u32x4*)(akb + (size_t)r * lda);
;       }
; #pragma unroll
;       for (int i = 0; i < 2; ++i) rb[i] = *(const u32x4*)(wp + (size_t)i * 64 * K);
;       if (TI == 5) rx = *(const u32x4*)(akb + (size_t)(arow - srow + 128) * lda);
;       if (++l_kt == nk) { l_kt = 0; l_id += G; }
;     };
;     ...
;     auto compute = [&](int buf) {
;       const unsigned char* Ab = As + buf * ASTG + (wn * 64 + lr) * 128;
;       const unsigned char* Ax = Ax0 + buf * 128;
;       const unsigned char* Bb = Bs + buf * 16384 + (wm * 64 + lr) * 128;
; #pragma unroll
;       for (int ks = 0; ks < 2; ++ks) {
;         if (TI == 5 && ks == 1) __builtin_amdgcn_sched_barrier(0);
;         const int sw = ((ks * 4 + lq) ^ (lr & 7)) << 4;
;         bf16x8 wf[4], xf[TI];
; #pragma unroll
;         for (int i = 0; i < 4; ++i) {
;           wf[i] = *(const bf16x8*)(Bb + i * 2048 + sw);
;           xf[i] = *(const bf16x8*)(Ab + i * 2048 + sw);
;         }
;         if (TI == 5) xf[TI - 1] = *(const bf16x8*)(Ax + ((ks * 4 + lq) << 4));
; #pragma unroll
;         for (int ni = 0; ni < 4; ++ni)
; #pragma unroll
;           for (int ti = 0; ti < 4; ++ti) acc[ni][ti] = MFMA16(wf[ni], xf[ti], acc[ni][ti]);
;         if (TI == 5) {
;           if (wn == 0) { acc[0][TI - 1] = MFMA16(wf[0], xf[TI - 1], acc[0][TI - 1]); acc[1][TI - 1] = MFMA16(wf[1], xf[TI - 1], acc[1][TI - 1]); }
;           else { acc[2][TI - 1] = MFMA16(wf[2], xf[TI - 1], acc[2][TI - 1]); acc[3][TI - 1] = MFMA16(wf[3], xf[TI - 1], acc[3][TI - 1]); }
;         }
;       }
;     };
.LBB0_607:
	s_and_b64 s[4:5], s[4:5], exec
	s_cselect_b32 s36, 0, s10
	s_waitcnt lgkmcnt(2)
	v_mfma_f32_16x16x32_bf16 v[18:21], v[0:3], v[4:7], v[26:29]
	s_cmp_lt_i32 s36, 2.0
	s_cselect_b32 s7, s43, 0
	s_cselect_b32 s10, s42, 0
	s_waitcnt lgkmcnt(0)
	v_mfma_f32_16x16x32_bf16 v[22:25], v[0:3], v[14:17], v[46:49]
	ds_read_b128 v[26:29], v130 offset:20480
	s_nop 1
	ds_read_b128 v[46:49], v130 offset:22528
	s_lshl_b32 s4, s36, 6
	s_ashr_i32 s5, s4, 31
	s_waitcnt lgkmcnt(1)
	v_mfma_f32_16x16x32_bf16 v[58:61], v[0:3], v[26:29], v[58:61]
	s_lshl_b64 s[4:5], s[4:5], 1
	v_mov_b32_e32 v115, v12
	v_lshl_add_u32 v130, s9, 7, v138
	s_waitcnt lgkmcnt(0)
	v_mfma_f32_16x16x32_bf16 v[0:3], v[0:3], v[46:49], v[62:65]
	s_mov_b32 s3, 0x20000
	s_mov_b32 s2, 0x30000
	v_mov_b32_e32 v117, v12
	v_mfma_f32_16x16x32_bf16 v[62:65], v[8:11], v[4:7], v[66:69]
	v_mfma_f32_16x16x32_bf16 v[66:69], v[8:11], v[14:17], v[70:73]
	v_mfma_f32_16x16x32_bf16 v[70:73], v[8:11], v[26:29], v[74:77]
	v_mfma_f32_16x16x32_bf16 v[8:11], v[8:11], v[46:49], v[78:81]
	s_nop 1
	ds_read_b128 v[74:77], v125 offset:53248
	ds_read_b128 v[78:81], v125 offset:55296
	ds_read_b128 v[180:183], v131 offset:16384
	s_waitcnt lgkmcnt(2)
	v_mfma_f32_16x16x32_bf16 v[132:135], v[74:77], v[4:7], v[82:85]
	s_waitcnt lgkmcnt(1)
	v_mfma_f32_16x16x32_bf16 v[168:171], v[78:81], v[4:7], v[102:105]
	ds_read_b128 v[4:7], v13 offset:49152
	v_mfma_f32_16x16x32_bf16 v[150:153], v[74:77], v[14:17], v[86:89]
	v_mfma_f32_16x16x32_bf16 v[158:161], v[74:77], v[46:49], v[110:113]
	v_mfma_f32_16x16x32_bf16 v[176:179], v[78:81], v[14:17], v[106:109]
	v_mfma_f32_16x16x32_bf16 v[202:205], v[78:81], v[46:49], v[98:101]
	ds_read_b128 v[14:17], v13 offset:51200
	ds_read_b128 v[46:49], v131 offset:18432
	ds_read_b128 v[206:209], v131 offset:22528
	v_mfma_f32_16x16x32_bf16 v[154:157], v[74:77], v[26:29], v[90:93]
	v_add_u32_e32 v74, s6, v139
	s_add_u32 s6, s10, s4
	s_addc_u32 s7, s7, s5
	s_waitcnt lgkmcnt(1)
	v_mfma_f32_16x16x32_bf16 v[106:109], v[4:7], v[46:49], v[22:25]
	v_lshl_add_u64 v[136:137], s[6:7], 0, v[114:115]
	s_add_i32 s8, s8, 2
	s_cmp_lg_u32 s8, 16
	v_min_i32_e32 v22, 0x407f, v74
	v_ashrrev_i32_e32 v23, 31, v22
	s_waitcnt lgkmcnt(0)
	v_mfma_f32_16x16x32_bf16 v[98:101], v[4:7], v[206:209], v[0:3]
	s_nop 2
	v_min_i32_e32 v2, 0x405f, v74
	v_mfma_f32_16x16x32_bf16 v[110:113], v[4:7], v[180:183], v[18:21]
	v_lshlrev_b64 v[0:1], 11, v[22:23]
	v_ashrrev_i32_e32 v3, 31, v2
	ds_read_b128 v[22:25], v13 offset:53248
	ds_read_b128 v[18:21], v131 offset:20480
	v_lshlrev_b64 v[2:3], 11, v[2:3]
	v_lshl_add_u64 v[2:3], v[136:137], 0, v[2:3]
	v_add_co_u32_e32 v2, vcc, s82, v2
	v_lshl_add_u64 v[0:1], v[136:137], 0, v[0:1]
	s_nop 0
	v_addc_co_u32_e32 v3, vcc, 0, v3, vcc
	s_waitcnt lgkmcnt(0)
	v_mfma_f32_16x16x32_bf16 v[102:105], v[4:7], v[18:21], v[58:61]
	global_load_dwordx4 v[4:7], v[0:1], off
	s_nop 0
	global_load_dwordx4 v[0:3], v[2:3], off
	v_min_i32_e32 v58, 0x403f, v74
	ds_read_b128 v[210:213], v13 offset:55296
	v_ashrrev_i32_e32 v59, 31, v58
	v_mfma_f32_16x16x32_bf16 v[82:85], v[14:17], v[206:209], v[8:11]
	v_ashrrev_i32_e32 v131, 31, v130
	s_nop 1
	v_lshlrev_b64 v[8:9], 11, v[58:59]
	v_min_i32_e32 v10, 0x401f, v74
	v_lshl_add_u64 v[8:9], v[136:137], 0, v[8:9]
	v_ashrrev_i32_e32 v11, 31, v10
	v_mfma_f32_16x16x32_bf16 v[26:29], v[78:81], v[26:29], v[94:97]
	v_add_co_u32_e32 v8, vcc, s3, v8
	v_lshlrev_b64 v[10:11], 11, v[10:11]
	v_mfma_f32_16x16x32_bf16 v[90:93], v[14:17], v[46:49], v[66:69]
	v_addc_co_u32_e32 v9, vcc, 0, v9, vcc
	v_lshl_add_u64 v[10:11], v[136:137], 0, v[10:11]
	v_mfma_f32_16x16x32_bf16 v[86:89], v[14:17], v[18:21], v[70:73]
	v_add_co_u32_e32 v10, vcc, s2, v10
	s_mov_b32 s2, 0x20000
	v_mfma_f32_16x16x32_bf16 v[78:81], v[22:25], v[180:183], v[132:135]
	v_addc_co_u32_e32 v11, vcc, 0, v11, vcc
	v_mfma_f32_16x16x32_bf16 v[74:77], v[22:25], v[46:49], v[150:153]
	v_mfma_f32_16x16x32_bf16 v[70:73], v[22:25], v[18:21], v[154:157]
	v_mfma_f32_16x16x32_bf16 v[66:69], v[22:25], v[206:209], v[158:161]
	v_lshlrev_b64 v[22:23], 11, v[130:131]
	v_lshl_add_u64 v[22:23], s[44:45], 0, v[22:23]
	v_lshl_add_u64 v[22:23], v[22:23], 0, s[4:5]
	v_lshl_add_u64 v[22:23], v[22:23], 0, v[116:117]
	v_add_co_u32_e32 v130, vcc, s3, v22
	v_mfma_f32_16x16x32_bf16 v[94:97], v[14:17], v[180:183], v[62:65]
	global_load_dwordx4 v[14:17], v[8:9], off
	s_nop 0
	global_load_dwordx4 v[8:11], v[10:11], off
	v_addc_co_u32_e32 v131, vcc, 0, v23, vcc
	s_waitcnt lgkmcnt(0)
	v_mfma_f32_16x16x32_bf16 v[58:61], v[210:213], v[46:49], v[176:179]
	v_mfma_f32_16x16x32_bf16 v[46:49], v[210:213], v[18:21], v[26:29]
	global_load_dwordx4 v[22:25], v[22:23], off
	s_nop 0
	global_load_dwordx4 v[18:21], v[130:131], off
	v_mfma_f32_16x16x32_bf16 v[62:65], v[210:213], v[180:183], v[168:171]
	v_mfma_f32_16x16x32_bf16 v[26:29], v[210:213], v[206:209], v[202:205]
	s_cbranch_scc1 .LBB0_627
	ds_read2_b32 v[132:133], v148 offset1:16
	ds_read2_b32 v[130:131], v148 offset0:32 offset1:48
	s_cmpk_gt_i32 s30, 0x3bf
	s_mov_b64 s[4:5], -1
	s_cbranch_scc0 .LBB0_611
	s_add_i32 s8, s30, 0xfffffc40
	s_movk_i32 s4, 0x4000
	s_cbranch_execz .LBB0_612

; __device__ __forceinline__ void rem_tile(int pos, int& mt, int& nt) { if (pos < 65) { mt = pos; nt = 40; } else { mt = 64; nt = pos - 65; } }
;     ...
;     auto issue = [&](u32x4 (&ra)[4], u32x4 (&rb)[2], u32x4& rx) {
;       const int idc = l_id < last_id ? l_id : last_id;
;       int mt, nt; if (TMAP == 1) rem_tile(idc, mt, nt); else tile_of(idc, ntn, mt, nt);
;       const bf16_t* A = (l_kt < ktsplit) ? A0 : A1;
;       const int kk = (l_kt < ktsplit) ? l_kt : l_kt - ktsplit;
;       const int arow = mt * 2 * BMH + hh * BMH + srow;
;     ...
;     auto compute = [&](int buf) {
;       const unsigned char* Ab = As + buf * ASTG + (wn * 64 + lr) * 128;
;       const unsigned char* Ax = Ax0 + buf * 128;
;       const unsigned char* Bb = Bs + buf * 16384 + (wm * 64 + lr) * 128;
; #pragma unroll
;       for (int ks = 0; ks < 2; ++ks) {
;         if (TI == 5 && ks == 1) __builtin_amdgcn_sched_barrier(0);
;         const int sw = ((ks * 4 + lq) ^ (lr & 7)) << 4;
;         bf16x8 wf[4], xf[TI];
; #pragma unroll
;         for (int i = 0; i < 4; ++i) {
;           wf[i] = *(const bf16x8*)(Bb + i * 2048 + sw);
;           xf[i] = *(const bf16x8*)(Ab + i * 2048 + sw);
;         }
.LBB0_698:
	v_add_u32_e32 v119, v133, v134
	ds_read_b128 v[30:33], v119 offset:32768
	v_add_u32_e32 v124, v132, v134
	ds_read_b128 v[34:37], v124
	ds_read_b128 v[38:41], v119 offset:34816
	ds_read_b128 v[42:45], v124 offset:2048
	s_min_i32 s46, s11, s35
	s_cmpk_gt_i32 s46, 0x2ff
	s_mov_b64 s[12:13], -1
	s_cbranch_scc0 .LBB0_700
	s_add_i32 s44, s46, 0xfffffd00
	s_mov_b64 s[12:13], 0

; #define MFMA16(a, b, c) __builtin_amdgcn_mfma_f32_16x16x32_bf16((a), (b), (c), 0, 0, 0)
;     ...
;     auto issue = [&](u32x4 (&ra)[4], u32x4 (&rb)[2], u32x4& rx) {
;       const int idc = l_id < last_id ? l_id : last_id;
;       int mt, nt; if (TMAP == 1) rem_tile(idc, mt, nt); else tile_of(idc, ntn, mt, nt);
;       const bf16_t* A = (l_kt < ktsplit) ? A0 : A1;
;       const int kk = (l_kt < ktsplit) ? l_kt : l_kt - ktsplit;
;       const int arow = mt * 2 * BMH + hh * BMH + srow;
;       const bf16_t* akb = A + kk * kstride + (tid & 7) * 8;
;       const bf16_t* wp = W + (size_t)(nt * 128 + wrow) * K + l_kt * 64 + (tid5 & 7) * 8;
; #pragma unroll
;       for (int i = 0; i < 4; ++i) {
;         int r = arow + 32 * i; r = r < M_ ? r : M_ - 1;
;         ra[i] = *(const u32x4*)(akb + (size_t)r * lda);
;       }
; #pragma unroll
;       for (int i = 0; i < 2; ++i) rb[i] = *(const u32x4*)(wp + (size_t)i * 64 * K);
;       if (TI == 5) rx = *(const u32x4*)(akb + (size_t)(arow - srow + 128) * lda);
;       if (++l_kt == nk) { l_kt = 0; l_id += G; }
;     };
;     ...
;     auto compute = [&](int buf) {
;       const unsigned char* Ab = As + buf * ASTG + (wn * 64 + lr) * 128;
;       const unsigned char* Ax = Ax0 + buf * 128;
;       const unsigned char* Bb = Bs + buf * 16384 + (wm * 64 + lr) * 128;
; #pragma unroll
;       for (int ks = 0; ks < 2; ++ks) {
;         if (TI == 5 && ks == 1) __builtin_amdgcn_sched_barrier(0);
;         const int sw = ((ks * 4 + lq) ^ (lr & 7)) << 4;
;         bf16x8 wf[4], xf[TI];
; #pragma unroll
;         for (int i = 0; i < 4; ++i) {
;           wf[i] = *(const bf16x8*)(Bb + i * 2048 + sw);
;           xf[i] = *(const bf16x8*)(Ab + i * 2048 + sw);
;         }
;         if (TI == 5) xf[TI - 1] = *(const bf16x8*)(Ax + ((ks * 4 + lq) << 4));
; #pragma unroll
;         for (int ni = 0; ni < 4; ++ni)
; #pragma unroll
;           for (int ti = 0; ti < 4; ++ti) acc[ni][ti] = MFMA16(wf[ni], xf[ti], acc[ni][ti]);
;         if (TI == 5) {
;           if (wn == 0) { acc[0][TI - 1] = MFMA16(wf[0], xf[TI - 1], acc[0][TI - 1]); acc[1][TI - 1] = MFMA16(wf[1], xf[TI - 1], acc[1][TI - 1]); }
;           else { acc[2][TI - 1] = MFMA16(wf[2], xf[TI - 1], acc[2][TI - 1]); acc[3][TI - 1] = MFMA16(wf[3], xf[TI - 1], acc[3][TI - 1]); }
;         }
;       }
;     };
.LBB0_702:
	s_cmp_lt_i32 s10, 2.0
	s_waitcnt lgkmcnt(1)
	v_mfma_f32_16x16x32_bf16 v[94:97], v[38:41], v[34:37], v[94:97]
	s_cselect_b32 s47, s5, 0
	s_cselect_b32 s46, s4, 0
	v_add_u32_e32 v117, s12, v129
	v_mfma_f32_16x16x32_bf16 v[50:53], v[30:33], v[34:37], v[110:113]
	s_lshl_b32 s12, s10, 6
	s_ashr_i32 s13, s12, 31
	s_lshl_b64 s[12:13], s[12:13], 1
	s_waitcnt lgkmcnt(0)
	v_mfma_f32_16x16x32_bf16 v[54:57], v[30:33], v[42:45], v[106:109]
	s_nop 2
	ds_read_b128 v[106:109], v124 offset:4096
	ds_read_b128 v[110:113], v124 offset:6144
	v_add_u32_e32 v13, v133, v135
	s_add_u32 s46, s46, s12
	s_waitcnt lgkmcnt(1)
	v_mfma_f32_16x16x32_bf16 v[102:105], v[30:33], v[106:109], v[102:105]
	s_addc_u32 s47, s47, s13
	v_mov_b32_e32 v115, v12
	s_mov_b32 s3, 0x8000
	s_waitcnt lgkmcnt(0)
	v_mfma_f32_16x16x32_bf16 v[30:33], v[30:33], v[110:113], v[98:101]
	v_add_u32_e32 v125, v132, v135
	s_waitcnt vmcnt(5)
	v_and_b32_e32 v127, 0xffff0000, v5
	s_waitcnt vmcnt(4)
	v_and_b32_e32 v126, 0xffff0000, v1
	v_mfma_f32_16x16x32_bf16 v[90:93], v[38:41], v[42:45], v[90:93]
	ds_read_b128 v[98:101], v119 offset:36864
	v_mfma_f32_16x16x32_bf16 v[86:89], v[38:41], v[106:109], v[86:89]
	v_mfma_f32_16x16x32_bf16 v[82:85], v[38:41], v[110:113], v[82:85]
	ds_read_b128 v[38:41], v119 offset:38912
	s_waitcnt lgkmcnt(0)
	v_mfma_f32_16x16x32_bf16 v[152:155], v[38:41], v[34:37], v[62:65]
	s_nop 2
	ds_read_b128 v[62:65], v13 offset:32768
	v_mfma_f32_16x16x32_bf16 v[140:143], v[98:101], v[34:37], v[78:81]
	v_min_i32_e32 v34, 0x405f, v117
	v_ashrrev_i32_e32 v35, 31, v34
	v_lshlrev_b64 v[34:35], 10, v[34:35]
	v_mfma_f32_16x16x32_bf16 v[144:147], v[98:101], v[42:45], v[74:77]
	s_nop 2
	v_lshl_add_u64 v[74:75], s[46:47], 0, v[114:115]
	v_mfma_f32_16x16x32_bf16 v[148:151], v[98:101], v[106:109], v[70:73]
	v_lshl_add_u64 v[34:35], v[74:75], 0, v[34:35]
	v_add_co_u32_e32 v34, vcc, s3, v34
	s_nop 0
	v_min_i32_e32 v70, 0x407f, v117
	v_ashrrev_i32_e32 v71, 31, v70
	v_mfma_f32_16x16x32_bf16 v[98:101], v[98:101], v[110:113], v[66:69]
	v_addc_co_u32_e32 v35, vcc, 0, v35, vcc
	v_lshl_add_u32 v76, s44, 7, v128
	s_nop 0
	v_lshlrev_b64 v[66:67], 10, v[70:71]
	v_lshl_add_u64 v[66:67], v[74:75], 0, v[66:67]
	v_mfma_f32_16x16x32_bf16 v[156:159], v[38:41], v[42:45], v[58:61]
	v_ashrrev_i32_e32 v77, 31, v76
	s_mov_b32 s44, 0x10000
	s_mov_b32 s3, 0x18000
	v_mfma_f32_16x16x32_bf16 v[160:163], v[38:41], v[106:109], v[46:49]
	ds_read_b128 v[106:109], v125
	global_load_dwordx4 v[42:45], v[66:67], off
	s_nop 0
	global_load_dwordx4 v[34:37], v[34:35], off
	ds_read_b128 v[78:81], v13 offset:34816
	ds_read_b128 v[176:179], v125 offset:2048
	ds_read_b128 v[180:183], v125 offset:4096
	ds_read_b128 v[202:205], v125 offset:6144
	v_mfma_f32_16x16x32_bf16 v[168:171], v[38:41], v[110:113], v[26:29]
	v_min_i32_e32 v38, 0x403f, v117
	v_ashrrev_i32_e32 v39, 31, v38
	v_lshlrev_b64 v[38:39], 10, v[38:39]
	v_min_i32_e32 v40, 0x401f, v117
	v_lshl_add_u64 v[38:39], v[74:75], 0, v[38:39]
	v_ashrrev_i32_e32 v41, 31, v40
	s_waitcnt lgkmcnt(4)
	v_mfma_f32_16x16x32_bf16 v[26:29], v[62:65], v[106:109], v[50:53]
	v_add_co_u32_e32 v38, vcc, s44, v38
	v_mov_b32_e32 v117, v12
	s_waitcnt lgkmcnt(2)
	v_mfma_f32_16x16x32_bf16 v[46:49], v[62:65], v[176:179], v[54:57]
	v_lshlrev_b64 v[50:51], 10, v[76:77]
	v_addc_co_u32_e32 v39, vcc, 0, v39, vcc
	s_waitcnt lgkmcnt(1)
	v_mfma_f32_16x16x32_bf16 v[58:61], v[62:65], v[180:183], v[102:105]
	v_lshl_add_u64 v[50:51], s[6:7], 0, v[50:51]
	v_lshl_add_u64 v[50:51], v[50:51], 0, s[12:13]
	v_lshl_add_u64 v[50:51], v[50:51], 0, v[116:117]
	s_waitcnt lgkmcnt(0)
	v_mfma_f32_16x16x32_bf16 v[62:65], v[62:65], v[202:205], v[30:33]
	v_and_b32_e32 v103, 0xffff0000, v4
	v_and_b32_e32 v102, 0xffff0000, v0
	s_add_i32 s47, s45, 1
	v_lshlrev_b64 v[30:31], 10, v[40:41]
	v_lshl_add_u64 v[30:31], v[74:75], 0, v[30:31]
	v_add_co_u32_e32 v30, vcc, s3, v30
	v_mfma_f32_16x16x32_bf16 v[66:69], v[78:81], v[106:109], v[94:97]
	s_nop 0
	v_addc_co_u32_e32 v31, vcc, 0, v31, vcc
	v_add_co_u32_e32 v52, vcc, s44, v50
	global_load_dwordx4 v[38:41], v[38:39], off
	s_nop 0
	global_load_dwordx4 v[30:33], v[30:31], off
	v_addc_co_u32_e32 v53, vcc, 0, v51, vcc
	ds_read_b128 v[94:97], v13 offset:36864
	ds_read_b128 v[206:209], v13 offset:38912
	global_load_dwordx4 v[54:57], v[50:51], off
	s_nop 0
	global_load_dwordx4 v[50:53], v[52:53], off
	v_mfma_f32_16x16x32_bf16 v[70:73], v[78:81], v[176:179], v[90:93]
	ds_write_b128 v131, v[4:7] offset:16384
	v_lshlrev_b32_e32 v5, 16, v5
	ds_write_b128 v131, v[0:3] offset:20480
	v_mfma_f32_16x16x32_bf16 v[74:77], v[78:81], v[180:183], v[86:89]
	s_cmp_lg_u32 s47, 8
	s_waitcnt vmcnt(9)
;     ...
;     auto store = [&](const u32x4 (&ra)[4], const u32x4 (&rb)[2], const u32x4& rx, int buf) {
; #pragma unroll
;       for (int i = 0; i < 4; ++i) {
;         if (RS) ss[i] += sumsq8(__builtin_bit_cast(bf16x8, ra[i]));
;         *(u32x4*)(As + buf * ASTG + i * 4096 + soff) = ra[i];
;       }
; #pragma unroll
;       for (int i = 0; i < 2; ++i) *(u32x4*)(Bs + buf * 16384 + i * 8192 + woff) = rb[i];
;       if (TI == 5) {
;         if (RS) ss[4] += sumsq8(__builtin_bit_cast(bf16x8, rx));
;         if (srow == 0) *(u32x4*)(Ax0 + buf * 128 + ((tid & 7) << 4)) = rx;
;       }
;       if (RS) {
;         if (++st_kt == nk) {
;           st_kt = 0;
; #pragma unroll
;           for (int i = 0; i < TI; ++i) {
;             float t = ss[i];
;             t += __shfl_xor(t, 1); t += __shfl_xor(t, 2); t += __shfl_xor(t, 4);
;             if ((tid & 7) == 0 && i < 4) rsl[srow + 32 * i] = rsqrtf(t * invK + EPS_);
;             ss[i] = 0.f;
;           }
;         }
;       }
;     };
	ds_write_b128 v131, v[14:17] offset:24576
	s_waitcnt vmcnt(8)
	ds_write_b128 v131, v[8:11] offset:28672
	s_waitcnt vmcnt(7)
	ds_write_b128 v130, v[22:25] offset:49152
	v_mfma_f32_16x16x32_bf16 v[78:81], v[78:81], v[202:205], v[82:85]
	s_waitcnt vmcnt(6)
	ds_write_b128 v130, v[18:21] offset:57344
	s_waitcnt lgkmcnt(7)
	v_mfma_f32_16x16x32_bf16 v[82:85], v[94:97], v[106:109], v[140:143]
	s_nop 2
	v_lshlrev_b32_e32 v141, 16, v4
	v_lshlrev_b32_e32 v140, 16, v0
	v_pk_mul_f32 v[142:143], v[102:103], v[102:103]
	v_mfma_f32_16x16x32_bf16 v[86:89], v[94:97], v[176:179], v[144:147]
	v_lshlrev_b32_e32 v4, 16, v1
	v_and_b32_e32 v1, 0xffff0000, v15
	v_and_b32_e32 v0, 0xffff0000, v9
	v_mfma_f32_16x16x32_bf16 v[90:93], v[94:97], v[180:183], v[148:151]
	v_mfma_f32_16x16x32_bf16 v[110:113], v[94:97], v[202:205], v[98:101]
	v_fma_f32 v94, v140, v140, v142
	v_fma_f32 v95, v141, v141, v143
	v_pk_fma_f32 v[4:5], v[4:5], v[4:5], v[94:95]
	v_lshlrev_b32_e32 v95, 16, v6
	v_pk_fma_f32 v[4:5], v[126:127], v[126:127], v[4:5]
	v_lshlrev_b32_e32 v94, 16, v2
	v_pk_fma_f32 v[4:5], v[94:95], v[94:95], v[4:5]
	v_and_b32_e32 v99, 0xffff0000, v6
	v_and_b32_e32 v98, 0xffff0000, v2
	v_pk_fma_f32 v[4:5], v[98:99], v[98:99], v[4:5]
	v_lshlrev_b32_e32 v127, 16, v7
	v_lshlrev_b32_e32 v126, 16, v3
	v_pk_fma_f32 v[4:5], v[126:127], v[126:127], v[4:5]
	v_and_b32_e32 v7, 0xffff0000, v7
	v_and_b32_e32 v6, 0xffff0000, v3
	v_pk_fma_f32 v[4:5], v[6:7], v[6:7], v[4:5]
	v_lshlrev_b32_e32 v3, 16, v14
	v_pk_add_f32 v[122:123], v[122:123], v[4:5]
	v_and_b32_e32 v5, 0xffff0000, v14
	v_and_b32_e32 v4, 0xffff0000, v8
	v_lshlrev_b32_e32 v2, 16, v8
	v_pk_mul_f32 v[4:5], v[4:5], v[4:5]
	v_lshlrev_b32_e32 v7, 16, v15
	v_lshlrev_b32_e32 v6, 16, v9
	v_pk_fma_f32 v[2:3], v[2:3], v[2:3], v[4:5]
	s_waitcnt lgkmcnt(6)
	v_mfma_f32_16x16x32_bf16 v[102:105], v[206:209], v[106:109], v[152:155]
	v_fma_f32 v2, v6, v6, v2
	v_fma_f32 v3, v7, v7, v3
	v_pk_fma_f32 v[0:1], v[0:1], v[0:1], v[2:3]
	v_lshlrev_b32_e32 v3, 16, v16
	v_lshlrev_b32_e32 v2, 16, v10
	v_pk_fma_f32 v[0:1], v[2:3], v[2:3], v[0:1]
	v_and_b32_e32 v3, 0xffff0000, v16
	v_and_b32_e32 v2, 0xffff0000, v10
	v_mfma_f32_16x16x32_bf16 v[106:109], v[206:209], v[176:179], v[156:159]
	v_fma_f32 v0, v2, v2, v0
	v_fma_f32 v1, v3, v3, v1
	v_lshlrev_b32_e32 v3, 16, v17
	v_lshlrev_b32_e32 v2, 16, v11
	v_mfma_f32_16x16x32_bf16 v[94:97], v[206:209], v[180:183], v[160:163]
	v_fma_f32 v0, v2, v2, v0
	v_fma_f32 v1, v3, v3, v1
	v_and_b32_e32 v3, 0xffff0000, v17
	v_and_b32_e32 v2, 0xffff0000, v11
	v_mfma_f32_16x16x32_bf16 v[98:101], v[206:209], v[202:205], v[168:171]
	v_fma_f32 v0, v2, v2, v0
	v_fma_f32 v1, v3, v3, v1
	v_pk_add_f32 v[120:121], v[120:121], v[0:1]
	s_cbranch_scc1 .LBB0_712
	v_and_b32_e32 v1, 64, v191
	v_xor_b32_e32 v0, 1, v191
	v_add_u32_e32 v2, 64, v1
	v_cmp_lt_i32_e32 vcc, v0, v2
	v_xor_b32_e32 v1, 2, v191
	v_xor_b32_e32 v5, 4, v191
	v_cndmask_b32_e32 v0, v191, v0, vcc
	v_lshlrev_b32_e32 v0, 2, v0
	ds_bpermute_b32 v3, v0, v123
	v_cmp_lt_i32_e32 vcc, v1, v2
	s_waitcnt lgkmcnt(0)
	v_add_f32_e32 v3, v123, v3
	v_cndmask_b32_e32 v1, v191, v1, vcc
	v_lshlrev_b32_e32 v1, 2, v1
	ds_bpermute_b32 v4, v1, v3
	v_cmp_lt_i32_e32 vcc, v5, v2
	s_waitcnt lgkmcnt(0)
	v_add_f32_e32 v3, v3, v4
	v_cndmask_b32_e32 v2, v191, v5, vcc
	v_lshlrev_b32_e32 v2, 2, v2
	ds_bpermute_b32 v4, v2, v3
	s_and_saveexec_b64 s[12:13], s[38:39]
	s_cbranch_execz .LBB0_705
	s_waitcnt lgkmcnt(0)
	v_add_f32_e32 v3, v3, v4
	v_fmamk_f32 v3, v3, 0x3b000000, v187
	v_mul_f32_e32 v4, 0x4b800000, v3
	v_cmp_gt_f32_e32 vcc, s33, v3
	s_nop 1
	v_cndmask_b32_e32 v3, v3, v4, vcc
	v_rsq_f32_e32 v3, v3
	s_nop 0
	v_mul_f32_e32 v4, 0x45800000, v3
	v_cndmask_b32_e32 v3, v3, v4, vcc
	ds_write_b32 v136, v3

; __device__ __forceinline__ void rem_tile(int pos, int& mt, int& nt) { if (pos < 65) { mt = pos; nt = 40; } else { mt = 64; nt = pos - 65; } }
;     ...
;     auto issue = [&](u32x4 (&ra)[4], u32x4 (&rb)[2], u32x4& rx) {
;       const int idc = l_id < last_id ? l_id : last_id;
;       int mt, nt; if (TMAP == 1) rem_tile(idc, mt, nt); else tile_of(idc, ntn, mt, nt);
;       const bf16_t* A = (l_kt < ktsplit) ? A0 : A1;
;       const int kk = (l_kt < ktsplit) ? l_kt : l_kt - ktsplit;
;       const int arow = mt * 2 * BMH + hh * BMH + srow;
;     ...
;     auto compute = [&](int buf) {
;       const unsigned char* Ab = As + buf * ASTG + (wn * 64 + lr) * 128;
;       const unsigned char* Ax = Ax0 + buf * 128;
;       const unsigned char* Bb = Bs + buf * 16384 + (wm * 64 + lr) * 128;
; #pragma unroll
;       for (int ks = 0; ks < 2; ++ks) {
;         if (TI == 5 && ks == 1) __builtin_amdgcn_sched_barrier(0);
;         const int sw = ((ks * 4 + lq) ^ (lr & 7)) << 4;
;         bf16x8 wf[4], xf[TI];
; #pragma unroll
;         for (int i = 0; i < 4; ++i) {
;           wf[i] = *(const bf16x8*)(Bb + i * 2048 + sw);
;           xf[i] = *(const bf16x8*)(Ab + i * 2048 + sw);
;         }
.LBB0_712:
	s_add_i32 s49, s10, 1
	s_cmp_eq_u32 s49, 8
	s_cselect_b64 s[12:13], -1, 0
	s_and_b64 s[44:45], s[12:13], exec
	s_load_dwordx2 s[44:45], s[0:1], 0x110
	s_waitcnt lgkmcnt(0)
	s_barrier
	ds_read_b128 v[0:3], v119 offset:49152
	ds_read_b128 v[4:7], v124 offset:16384
	ds_read_b128 v[8:11], v119 offset:51200
	ds_read_b128 v[14:17], v124 offset:18432
	s_cselect_b32 s46, s44, 0
	s_add_i32 s46, s46, s11
	s_min_i32 s52, s46, s35
	s_cmpk_gt_i32 s52, 0x2ff
	s_mov_b64 s[44:45], -1
	s_cbranch_scc0 .LBB0_714
	s_add_i32 s10, s52, 0xfffffd00
	s_mov_b64 s[44:45], 0

; #define MFMA16(a, b, c) __builtin_amdgcn_mfma_f32_16x16x32_bf16((a), (b), (c), 0, 0, 0)
;     ...
;     auto issue = [&](u32x4 (&ra)[4], u32x4 (&rb)[2], u32x4& rx) {
;       const int idc = l_id < last_id ? l_id : last_id;
;       int mt, nt; if (TMAP == 1) rem_tile(idc, mt, nt); else tile_of(idc, ntn, mt, nt);
;       const bf16_t* A = (l_kt < ktsplit) ? A0 : A1;
;       const int kk = (l_kt < ktsplit) ? l_kt : l_kt - ktsplit;
;       const int arow = mt * 2 * BMH + hh * BMH + srow;
;       const bf16_t* akb = A + kk * kstride + (tid & 7) * 8;
;       const bf16_t* wp = W + (size_t)(nt * 128 + wrow) * K + l_kt * 64 + (tid5 & 7) * 8;
; #pragma unroll
;       for (int i = 0; i < 4; ++i) {
;         int r = arow + 32 * i; r = r < M_ ? r : M_ - 1;
;         ra[i] = *(const u32x4*)(akb + (size_t)r * lda);
;       }
; #pragma unroll
;       for (int i = 0; i < 2; ++i) rb[i] = *(const u32x4*)(wp + (size_t)i * 64 * K);
;       if (TI == 5) rx = *(const u32x4*)(akb + (size_t)(arow - srow + 128) * lda);
;       if (++l_kt == nk) { l_kt = 0; l_id += G; }
;     };
;     ...
;     auto compute = [&](int buf) {
;       const unsigned char* Ab = As + buf * ASTG + (wn * 64 + lr) * 128;
;       const unsigned char* Ax = Ax0 + buf * 128;
;       const unsigned char* Bb = Bs + buf * 16384 + (wm * 64 + lr) * 128;
; #pragma unroll
;       for (int ks = 0; ks < 2; ++ks) {
;         if (TI == 5 && ks == 1) __builtin_amdgcn_sched_barrier(0);
;         const int sw = ((ks * 4 + lq) ^ (lr & 7)) << 4;
;         bf16x8 wf[4], xf[TI];
; #pragma unroll
;         for (int i = 0; i < 4; ++i) {
;           wf[i] = *(const bf16x8*)(Bb + i * 2048 + sw);
;           xf[i] = *(const bf16x8*)(Ab + i * 2048 + sw);
;         }
;         if (TI == 5) xf[TI - 1] = *(const bf16x8*)(Ax + ((ks * 4 + lq) << 4));
; #pragma unroll
;         for (int ni = 0; ni < 4; ++ni)
; #pragma unroll
;           for (int ti = 0; ti < 4; ++ti) acc[ni][ti] = MFMA16(wf[ni], xf[ti], acc[ni][ti]);
;         if (TI == 5) {
;           if (wn == 0) { acc[0][TI - 1] = MFMA16(wf[0], xf[TI - 1], acc[0][TI - 1]); acc[1][TI - 1] = MFMA16(wf[1], xf[TI - 1], acc[1][TI - 1]); }
;           else { acc[2][TI - 1] = MFMA16(wf[2], xf[TI - 1], acc[2][TI - 1]); acc[3][TI - 1] = MFMA16(wf[3], xf[TI - 1], acc[3][TI - 1]); }
;         }
;       }
;     };
.LBB0_716:
	s_and_b64 s[12:13], s[12:13], exec
	s_cselect_b32 s44, 0, s49
	s_waitcnt lgkmcnt(2)
	v_mfma_f32_16x16x32_bf16 v[18:21], v[0:3], v[4:7], v[26:29]
	s_cmp_lt_i32 s44, 2.0
	s_cselect_b32 s45, s5, 0
	s_cselect_b32 s49, s4, 0
	s_waitcnt lgkmcnt(0)
	v_mfma_f32_16x16x32_bf16 v[22:25], v[0:3], v[14:17], v[46:49]
	ds_read_b128 v[26:29], v124 offset:20480
	s_nop 1
	ds_read_b128 v[46:49], v124 offset:22528
	s_lshl_b32 s12, s44, 6
	s_ashr_i32 s13, s12, 31
	s_waitcnt lgkmcnt(1)
	v_mfma_f32_16x16x32_bf16 v[58:61], v[0:3], v[26:29], v[58:61]
	s_lshl_b64 s[12:13], s[12:13], 1
	s_add_u32 s52, s49, s12
	s_addc_u32 s53, s45, s13
	s_waitcnt lgkmcnt(0)
	v_mfma_f32_16x16x32_bf16 v[0:3], v[0:3], v[46:49], v[62:65]
	v_mov_b32_e32 v115, v12
	v_lshl_add_u64 v[172:173], s[52:53], 0, v[114:115]
	s_mov_b32 s3, 0x8000
	v_mfma_f32_16x16x32_bf16 v[62:65], v[8:11], v[4:7], v[66:69]
	v_lshl_add_u32 v184, s10, 7, v128
	v_ashrrev_i32_e32 v185, 31, v184
	s_mov_b32 s10, 0x10000
	v_mfma_f32_16x16x32_bf16 v[66:69], v[8:11], v[14:17], v[70:73]
	v_mov_b32_e32 v117, v12
	s_add_i32 s37, s37, 2
	s_mov_b32 s82, 0x10000
	v_mfma_f32_16x16x32_bf16 v[70:73], v[8:11], v[26:29], v[74:77]
	s_cmp_lg_u32 s37, 8
	v_mfma_f32_16x16x32_bf16 v[8:11], v[8:11], v[46:49], v[78:81]
	s_nop 0
	ds_read_b128 v[74:77], v119 offset:53248
	s_nop 0
	ds_read_b128 v[78:81], v119 offset:55296
	ds_read_b128 v[168:171], v125 offset:16384
	s_waitcnt lgkmcnt(2)
	v_mfma_f32_16x16x32_bf16 v[140:143], v[74:77], v[4:7], v[82:85]
	s_waitcnt lgkmcnt(1)
	v_mfma_f32_16x16x32_bf16 v[156:159], v[78:81], v[4:7], v[102:105]
	ds_read_b128 v[4:7], v13 offset:49152
	v_mfma_f32_16x16x32_bf16 v[144:147], v[74:77], v[14:17], v[86:89]
	v_mfma_f32_16x16x32_bf16 v[152:155], v[74:77], v[46:49], v[110:113]
	v_mfma_f32_16x16x32_bf16 v[160:163], v[78:81], v[14:17], v[106:109]
	v_mfma_f32_16x16x32_bf16 v[176:179], v[78:81], v[46:49], v[98:101]
	ds_read_b128 v[14:17], v13 offset:51200
	ds_read_b128 v[46:49], v125 offset:18432
	s_waitcnt lgkmcnt(2)
	v_mfma_f32_16x16x32_bf16 v[110:113], v[4:7], v[168:171], v[18:21]
	s_nop 2
	ds_read_b128 v[18:21], v125 offset:20480
	ds_read_b128 v[124:127], v125 offset:22528
	v_mfma_f32_16x16x32_bf16 v[148:151], v[74:77], v[26:29], v[90:93]
	v_add_u32_e32 v74, s11, v129
	s_waitcnt lgkmcnt(2)
	v_mfma_f32_16x16x32_bf16 v[106:109], v[4:7], v[46:49], v[22:25]
	s_nop 2
	v_min_i32_e32 v22, 0x407f, v74
	v_ashrrev_i32_e32 v23, 31, v22
	s_waitcnt lgkmcnt(0)
	v_mfma_f32_16x16x32_bf16 v[98:101], v[4:7], v[124:127], v[0:3]
	s_nop 2
	v_min_i32_e32 v2, 0x405f, v74
	v_lshlrev_b64 v[0:1], 10, v[22:23]
	v_ashrrev_i32_e32 v3, 31, v2
	ds_read_b128 v[22:25], v13 offset:53248
	v_lshlrev_b64 v[2:3], 10, v[2:3]
	v_lshl_add_u64 v[2:3], v[172:173], 0, v[2:3]
	v_add_co_u32_e32 v2, vcc, s3, v2
	v_lshl_add_u64 v[0:1], v[172:173], 0, v[0:1]
	s_nop 0
	v_addc_co_u32_e32 v3, vcc, 0, v3, vcc
	v_mfma_f32_16x16x32_bf16 v[102:105], v[4:7], v[18:21], v[58:61]
	global_load_dwordx4 v[4:7], v[0:1], off
	s_nop 0
	global_load_dwordx4 v[0:3], v[2:3], off
	v_min_i32_e32 v58, 0x403f, v74
	ds_read_b128 v[180:183], v13 offset:55296
	v_ashrrev_i32_e32 v59, 31, v58
	v_mfma_f32_16x16x32_bf16 v[82:85], v[14:17], v[124:127], v[8:11]
	s_mov_b32 s3, 0x18000
	s_nop 1
	v_lshlrev_b64 v[8:9], 10, v[58:59]
	v_min_i32_e32 v10, 0x401f, v74
	v_lshl_add_u64 v[8:9], v[172:173], 0, v[8:9]
	v_ashrrev_i32_e32 v11, 31, v10
	v_mfma_f32_16x16x32_bf16 v[26:29], v[78:81], v[26:29], v[94:97]
	v_add_co_u32_e32 v8, vcc, s10, v8
	v_lshlrev_b64 v[10:11], 10, v[10:11]
	v_mfma_f32_16x16x32_bf16 v[90:93], v[14:17], v[46:49], v[66:69]
	v_addc_co_u32_e32 v9, vcc, 0, v9, vcc
	v_lshl_add_u64 v[10:11], v[172:173], 0, v[10:11]
	v_mfma_f32_16x16x32_bf16 v[86:89], v[14:17], v[18:21], v[70:73]
	v_add_co_u32_e32 v10, vcc, s3, v10
	s_waitcnt lgkmcnt(1)
	v_mfma_f32_16x16x32_bf16 v[78:81], v[22:25], v[168:171], v[140:143]
	v_addc_co_u32_e32 v11, vcc, 0, v11, vcc
	v_mfma_f32_16x16x32_bf16 v[74:77], v[22:25], v[46:49], v[144:147]
	v_mfma_f32_16x16x32_bf16 v[70:73], v[22:25], v[18:21], v[148:151]
	v_mfma_f32_16x16x32_bf16 v[66:69], v[22:25], v[124:127], v[152:155]
	v_lshlrev_b64 v[22:23], 10, v[184:185]
	v_lshl_add_u64 v[22:23], s[6:7], 0, v[22:23]
	v_lshl_add_u64 v[22:23], v[22:23], 0, s[12:13]
	v_lshl_add_u64 v[22:23], v[22:23], 0, v[116:117]
	v_add_co_u32_e32 v140, vcc, s10, v22
	v_mfma_f32_16x16x32_bf16 v[94:97], v[14:17], v[168:171], v[62:65]
	global_load_dwordx4 v[14:17], v[8:9], off
	s_nop 0
	global_load_dwordx4 v[8:11], v[10:11], off
	v_addc_co_u32_e32 v141, vcc, 0, v23, vcc
	s_waitcnt lgkmcnt(0)
	v_mfma_f32_16x16x32_bf16 v[58:61], v[180:183], v[46:49], v[160:163]
	v_mfma_f32_16x16x32_bf16 v[46:49], v[180:183], v[18:21], v[26:29]
	global_load_dwordx4 v[22:25], v[22:23], off
	s_nop 0
	global_load_dwordx4 v[18:21], v[140:141], off
	v_mfma_f32_16x16x32_bf16 v[62:65], v[180:183], v[168:171], v[156:159]
	v_mfma_f32_16x16x32_bf16 v[26:29], v[180:183], v[124:127], v[176:179]
	s_cbranch_scc1 .LBB0_722
	ds_read2_b32 v[126:127], v138 offset1:16
	ds_read2_b32 v[124:125], v138 offset0:32 offset1:48
	s_cmpk_gt_i32 s34, 0x2ff
	s_mov_b64 s[12:13], -1
	s_cbranch_scc0 .LBB0_731
	s_add_i32 s10, s34, 0xfffffd00
	s_movk_i32 s11, 0x4000
	s_cbranch_execz .LBB0_732

; __device__ __forceinline__ void rem_tile(int pos, int& mt, int& nt) { if (pos < 65) { mt = pos; nt = 40; } else { mt = 64; nt = pos - 65; } }
;     ...
;     auto issue = [&](u32x4 (&ra)[4], u32x4 (&rb)[2], u32x4& rx) {
;       const int idc = l_id < last_id ? l_id : last_id;
;       int mt, nt; if (TMAP == 1) rem_tile(idc, mt, nt); else tile_of(idc, ntn, mt, nt);
;       const bf16_t* A = (l_kt < ktsplit) ? A0 : A1;
;       const int kk = (l_kt < ktsplit) ? l_kt : l_kt - ktsplit;
;       const int arow = mt * 2 * BMH + hh * BMH + srow;
;     ...
;     auto compute = [&](int buf) {
;       const unsigned char* Ab = As + buf * ASTG + (wn * 64 + lr) * 128;
;       const unsigned char* Ax = Ax0 + buf * 128;
;       const unsigned char* Bb = Bs + buf * 16384 + (wm * 64 + lr) * 128;
; #pragma unroll
;       for (int ks = 0; ks < 2; ++ks) {
;         if (TI == 5 && ks == 1) __builtin_amdgcn_sched_barrier(0);
;         const int sw = ((ks * 4 + lq) ^ (lr & 7)) << 4;
;         bf16x8 wf[4], xf[TI];
; #pragma unroll
;         for (int i = 0; i < 4; ++i) {
;           wf[i] = *(const bf16x8*)(Bb + i * 2048 + sw);
;           xf[i] = *(const bf16x8*)(Ab + i * 2048 + sw);
;         }
.LBB0_746:
	v_add_u32_e32 v121, v139, v140
	ds_read_b128 v[26:29], v121 offset:32768
	v_add_u32_e32 v126, v138, v140
	ds_read_b128 v[30:33], v126
	ds_read_b128 v[34:37], v121 offset:34816
	ds_read_b128 v[38:41], v126 offset:2048
	s_min_i32 s10, s7, s13
	s_cmpk_gt_i32 s10, 0x3ff
	s_mov_b64 s[4:5], -1
	s_cbranch_scc0 .LBB0_748
	s_add_i32 s8, s10, 0xfffffc00
	s_mov_b64 s[4:5], 0

; #define MFMA16(a, b, c) __builtin_amdgcn_mfma_f32_16x16x32_bf16((a), (b), (c), 0, 0, 0)
;     ...
;     auto issue = [&](u32x4 (&ra)[4], u32x4 (&rb)[2], u32x4& rx) {
;       const int idc = l_id < last_id ? l_id : last_id;
;       int mt, nt; if (TMAP == 1) rem_tile(idc, mt, nt); else tile_of(idc, ntn, mt, nt);
;       const bf16_t* A = (l_kt < ktsplit) ? A0 : A1;
;       const int kk = (l_kt < ktsplit) ? l_kt : l_kt - ktsplit;
;       const int arow = mt * 2 * BMH + hh * BMH + srow;
;       const bf16_t* akb = A + kk * kstride + (tid & 7) * 8;
;       const bf16_t* wp = W + (size_t)(nt * 128 + wrow) * K + l_kt * 64 + (tid5 & 7) * 8;
; #pragma unroll
;       for (int i = 0; i < 4; ++i) {
;         int r = arow + 32 * i; r = r < M_ ? r : M_ - 1;
;         ra[i] = *(const u32x4*)(akb + (size_t)r * lda);
;       }
; #pragma unroll
;       for (int i = 0; i < 2; ++i) rb[i] = *(const u32x4*)(wp + (size_t)i * 64 * K);
;       if (TI == 5) rx = *(const u32x4*)(akb + (size_t)(arow - srow + 128) * lda);
;       if (++l_kt == nk) { l_kt = 0; l_id += G; }
;     };
;     ...
;     auto compute = [&](int buf) {
;       const unsigned char* Ab = As + buf * ASTG + (wn * 64 + lr) * 128;
;       const unsigned char* Ax = Ax0 + buf * 128;
;       const unsigned char* Bb = Bs + buf * 16384 + (wm * 64 + lr) * 128;
; #pragma unroll
;       for (int ks = 0; ks < 2; ++ks) {
;         if (TI == 5 && ks == 1) __builtin_amdgcn_sched_barrier(0);
;         const int sw = ((ks * 4 + lq) ^ (lr & 7)) << 4;
;         bf16x8 wf[4], xf[TI];
; #pragma unroll
;         for (int i = 0; i < 4; ++i) {
;           wf[i] = *(const bf16x8*)(Bb + i * 2048 + sw);
;           xf[i] = *(const bf16x8*)(Ab + i * 2048 + sw);
;         }
;         if (TI == 5) xf[TI - 1] = *(const bf16x8*)(Ax + ((ks * 4 + lq) << 4));
; #pragma unroll
;         for (int ni = 0; ni < 4; ++ni)
; #pragma unroll
;           for (int ti = 0; ti < 4; ++ti) acc[ni][ti] = MFMA16(wf[ni], xf[ti], acc[ni][ti]);
;         if (TI == 5) {
;           if (wn == 0) { acc[0][TI - 1] = MFMA16(wf[0], xf[TI - 1], acc[0][TI - 1]); acc[1][TI - 1] = MFMA16(wf[1], xf[TI - 1], acc[1][TI - 1]); }
;           else { acc[2][TI - 1] = MFMA16(wf[2], xf[TI - 1], acc[2][TI - 1]); acc[3][TI - 1] = MFMA16(wf[3], xf[TI - 1], acc[3][TI - 1]); }
;         }
;       }
;     };
.LBB0_750:
	s_cmp_lt_i32 s6, 2.0
	s_cselect_b32 s11, s43, 0
	s_waitcnt lgkmcnt(0)
	v_mfma_f32_16x16x32_bf16 v[94:97], v[34:37], v[38:41], v[94:97]
	s_cselect_b32 s10, s42, 0
	v_add_u32_e32 v117, s4, v135
	s_lshl_b32 s4, s6, 6
	v_mfma_f32_16x16x32_bf16 v[42:45], v[26:29], v[30:33], v[110:113]
	s_ashr_i32 s5, s4, 31
	s_lshl_b64 s[4:5], s[4:5], 1
	v_add_u32_e32 v13, v139, v141
	v_mfma_f32_16x16x32_bf16 v[46:49], v[26:29], v[38:41], v[102:105]
	s_nop 2
	ds_read_b128 v[102:105], v126 offset:4096
	ds_read_b128 v[110:113], v126 offset:6144
	s_add_u32 s10, s10, s4
	s_addc_u32 s11, s11, s5
	s_waitcnt lgkmcnt(1)
	v_mfma_f32_16x16x32_bf16 v[86:89], v[26:29], v[102:105], v[86:89]
	v_mov_b32_e32 v115, v12
	v_lshl_add_u64 v[132:133], s[10:11], 0, v[114:115]
	s_movk_i32 s3, 0x4000
	s_waitcnt lgkmcnt(0)
	v_mfma_f32_16x16x32_bf16 v[26:29], v[26:29], v[110:113], v[70:73]
	v_add_u32_e32 v127, v138, v141
	v_lshl_add_u32 v162, s8, 7, v134
	v_ashrrev_i32_e32 v163, 31, v162
	v_mfma_f32_16x16x32_bf16 v[70:73], v[34:37], v[30:33], v[106:109]
	s_mov_b32 s8, 0xc000
	s_add_i32 s9, s9, 1
	s_cmp_lg_u32 s9, 4
	ds_read_b128 v[106:109], v121 offset:36864
	v_mfma_f32_16x16x32_bf16 v[78:81], v[34:37], v[102:105], v[78:81]
	v_mfma_f32_16x16x32_bf16 v[128:131], v[34:37], v[110:113], v[62:65]
	ds_read_b128 v[34:37], v121 offset:38912
	s_nop 1
	v_min_i32_e32 v62, 0x407f, v117
	v_ashrrev_i32_e32 v63, 31, v62
	s_waitcnt lgkmcnt(1)
	v_mfma_f32_16x16x32_bf16 v[98:101], v[106:109], v[30:33], v[98:101]
	v_mfma_f32_16x16x32_bf16 v[146:149], v[106:109], v[38:41], v[82:85]
	v_mfma_f32_16x16x32_bf16 v[150:153], v[106:109], v[102:105], v[66:69]
	v_mfma_f32_16x16x32_bf16 v[106:109], v[106:109], v[110:113], v[54:57]
	s_nop 2
	v_lshlrev_b64 v[54:55], 9, v[62:63]
	ds_read_b128 v[62:65], v13 offset:32768
	s_waitcnt lgkmcnt(1)
	v_mfma_f32_16x16x32_bf16 v[154:157], v[34:37], v[30:33], v[90:93]
	v_min_i32_e32 v30, 0x405f, v117
	v_ashrrev_i32_e32 v31, 31, v30
	v_lshlrev_b64 v[30:31], 9, v[30:31]
	v_lshl_add_u64 v[30:31], v[132:133], 0, v[30:31]
	v_add_co_u32_e32 v30, vcc, s3, v30
	v_lshl_add_u64 v[54:55], v[132:133], 0, v[54:55]
	s_nop 0
	v_addc_co_u32_e32 v31, vcc, 0, v31, vcc
	v_mfma_f32_16x16x32_bf16 v[158:161], v[34:37], v[38:41], v[74:77]
	s_mov_b32 s3, 0x8000
	v_mfma_f32_16x16x32_bf16 v[168:171], v[34:37], v[102:105], v[58:61]
	ds_read_b128 v[102:105], v127
	global_load_dwordx4 v[38:41], v[54:55], off
	s_nop 0
	global_load_dwordx4 v[30:33], v[30:31], off
	ds_read_b128 v[82:85], v13 offset:34816
	ds_read_b128 v[180:183], v127 offset:2048
	ds_read_b128 v[202:205], v127 offset:4096
	ds_read_b128 v[206:209], v127 offset:6144
	v_mfma_f32_16x16x32_bf16 v[176:179], v[34:37], v[110:113], v[50:53]
	v_min_i32_e32 v34, 0x403f, v117
	v_ashrrev_i32_e32 v35, 31, v34
	v_lshlrev_b64 v[34:35], 9, v[34:35]
	v_min_i32_e32 v36, 0x401f, v117
	v_lshl_add_u64 v[34:35], v[132:133], 0, v[34:35]
	v_ashrrev_i32_e32 v37, 31, v36
	s_waitcnt lgkmcnt(4)
	v_mfma_f32_16x16x32_bf16 v[50:53], v[62:65], v[102:105], v[42:45]
	v_add_co_u32_e32 v34, vcc, s3, v34
	v_mov_b32_e32 v117, v12
	s_waitcnt lgkmcnt(2)
	v_mfma_f32_16x16x32_bf16 v[54:57], v[62:65], v[180:183], v[46:49]
	v_lshlrev_b64 v[42:43], 9, v[162:163]
	v_addc_co_u32_e32 v35, vcc, 0, v35, vcc
	s_waitcnt lgkmcnt(1)
	v_mfma_f32_16x16x32_bf16 v[58:61], v[62:65], v[202:205], v[86:89]
	v_lshl_add_u64 v[42:43], s[44:45], 0, v[42:43]
	v_lshl_add_u64 v[42:43], v[42:43], 0, s[4:5]
	v_lshl_add_u64 v[42:43], v[42:43], 0, v[116:117]
	s_waitcnt lgkmcnt(0)
	v_mfma_f32_16x16x32_bf16 v[62:65], v[62:65], v[206:209], v[26:29]
	s_waitcnt vmcnt(7)
	v_and_b32_e32 v111, 0xffff0000, v4
	s_waitcnt vmcnt(6)
	v_and_b32_e32 v110, 0xffff0000, v0
	v_lshlrev_b64 v[26:27], 9, v[36:37]
	v_lshl_add_u64 v[26:27], v[132:133], 0, v[26:27]
	v_add_co_u32_e32 v26, vcc, s8, v26
	v_mfma_f32_16x16x32_bf16 v[66:69], v[82:85], v[102:105], v[70:73]
	s_nop 0
	v_addc_co_u32_e32 v27, vcc, 0, v27, vcc
	v_add_co_u32_e32 v44, vcc, s3, v42
	global_load_dwordx4 v[34:37], v[34:35], off
	s_nop 0
	global_load_dwordx4 v[26:29], v[26:27], off
	v_addc_co_u32_e32 v45, vcc, 0, v43, vcc
	v_mfma_f32_16x16x32_bf16 v[70:73], v[82:85], v[180:183], v[94:97]
	v_mul_f32_e64 v132, v110, v110
	v_mul_f32_e64 v133, v111, v111
	v_mfma_f32_16x16x32_bf16 v[74:77], v[82:85], v[202:205], v[78:81]
	ds_read_b128 v[94:97], v13 offset:36864
	v_mfma_f32_16x16x32_bf16 v[78:81], v[82:85], v[206:209], v[128:131]
	s_nop 2
	ds_read_b128 v[128:131], v13 offset:38912
	global_load_dwordx4 v[46:49], v[42:43], off
	s_nop 0
	global_load_dwordx4 v[42:45], v[44:45], off
	s_waitcnt lgkmcnt(1)
;     ...
;     auto store = [&](const u32x4 (&ra)[4], const u32x4 (&rb)[2], const u32x4& rx, int buf) {
; #pragma unroll
;       for (int i = 0; i < 4; ++i) {
;         if (RS) ss[i] += sumsq8(__builtin_bit_cast(bf16x8, ra[i]));
;         *(u32x4*)(As + buf * ASTG + i * 4096 + soff) = ra[i];
;       }
; #pragma unroll
;       for (int i = 0; i < 2; ++i) *(u32x4*)(Bs + buf * 16384 + i * 8192 + woff) = rb[i];
;       if (TI == 5) {
;         if (RS) ss[4] += sumsq8(__builtin_bit_cast(bf16x8, rx));
;         if (srow == 0) *(u32x4*)(Ax0 + buf * 128 + ((tid & 7) << 4)) = rx;
;       }
;       if (RS) {
;         if (++st_kt == nk) {
;           st_kt = 0;
; #pragma unroll
;           for (int i = 0; i < TI; ++i) {
;             float t = ss[i];
;             t += __shfl_xor(t, 1); t += __shfl_xor(t, 2); t += __shfl_xor(t, 4);
;             if ((tid & 7) == 0 && i < 4) rsl[srow + 32 * i] = rsqrtf(t * invK + EPS_);
;             ss[i] = 0.f;
;           }
;         }
;       }
;     };
	v_mfma_f32_16x16x32_bf16 v[82:85], v[94:97], v[102:105], v[98:101]
	ds_write_b128 v137, v[4:7] offset:16384
	ds_write_b128 v137, v[0:3] offset:20480
	s_waitcnt vmcnt(9)
	ds_write_b128 v137, v[14:17] offset:24576
	v_lshlrev_b32_e32 v101, 16, v4
	v_lshlrev_b32_e32 v100, 16, v0
	v_and_b32_e32 v99, 0xffff0000, v5
	v_mfma_f32_16x16x32_bf16 v[86:89], v[94:97], v[180:183], v[146:149]
	v_lshlrev_b32_e32 v5, 16, v5
	v_lshlrev_b32_e32 v4, 16, v1
	v_and_b32_e32 v98, 0xffff0000, v1
	v_mfma_f32_16x16x32_bf16 v[90:93], v[94:97], v[202:205], v[150:153]
	v_and_b32_e32 v1, 0xffff0000, v15
	s_waitcnt vmcnt(8)
	v_and_b32_e32 v0, 0xffff0000, v9
	ds_write_b128 v137, v[8:11] offset:28672
	s_waitcnt vmcnt(7)
	ds_write_b128 v136, v[22:25] offset:49152
	v_mfma_f32_16x16x32_bf16 v[110:113], v[94:97], v[206:209], v[106:109]
	v_fma_f32 v94, v100, v100, v132
	v_fma_f32 v95, v101, v101, v133
	s_waitcnt vmcnt(6)
	ds_write_b128 v136, v[18:21] offset:57344
	v_pk_fma_f32 v[4:5], v[4:5], v[4:5], v[94:95]
	v_lshlrev_b32_e32 v95, 16, v6
	v_pk_fma_f32 v[4:5], v[98:99], v[98:99], v[4:5]
	v_lshlrev_b32_e32 v94, 16, v2
	v_pk_fma_f32 v[4:5], v[94:95], v[94:95], v[4:5]
	v_and_b32_e32 v99, 0xffff0000, v6
	v_and_b32_e32 v98, 0xffff0000, v2
	s_waitcnt lgkmcnt(6)
	v_mfma_f32_16x16x32_bf16 v[102:105], v[128:131], v[102:105], v[154:157]
	v_fma_f32 v4, v98, v98, v4
	v_fma_f32 v5, v99, v99, v5
	v_and_b32_e32 v6, 0xffff0000, v3
	v_lshlrev_b32_e32 v2, 16, v8
	v_mfma_f32_16x16x32_bf16 v[106:109], v[128:131], v[180:183], v[158:161]
	v_mfma_f32_16x16x32_bf16 v[94:97], v[128:131], v[202:205], v[168:171]
	v_mfma_f32_16x16x32_bf16 v[98:101], v[128:131], v[206:209], v[176:179]
	v_lshlrev_b32_e32 v129, 16, v7
	v_lshlrev_b32_e32 v128, 16, v3
	v_pk_fma_f32 v[4:5], v[128:129], v[128:129], v[4:5]
	v_and_b32_e32 v7, 0xffff0000, v7
	v_pk_fma_f32 v[4:5], v[6:7], v[6:7], v[4:5]
	v_lshlrev_b32_e32 v3, 16, v14
	v_pk_add_f32 v[124:125], v[124:125], v[4:5]
	v_and_b32_e32 v5, 0xffff0000, v14
	v_and_b32_e32 v4, 0xffff0000, v8
	v_pk_mul_f32 v[4:5], v[4:5], v[4:5]
	v_lshlrev_b32_e32 v7, 16, v15
	v_lshlrev_b32_e32 v6, 16, v9
	v_pk_fma_f32 v[2:3], v[2:3], v[2:3], v[4:5]
	s_nop 0
	v_pk_fma_f32 v[2:3], v[6:7], v[6:7], v[2:3]
	s_nop 0
	v_pk_fma_f32 v[0:1], v[0:1], v[0:1], v[2:3]
	v_lshlrev_b32_e32 v3, 16, v16
	v_lshlrev_b32_e32 v2, 16, v10
	v_pk_fma_f32 v[0:1], v[2:3], v[2:3], v[0:1]
	v_and_b32_e32 v3, 0xffff0000, v16
	v_and_b32_e32 v2, 0xffff0000, v10
	v_pk_fma_f32 v[0:1], v[2:3], v[2:3], v[0:1]
	v_lshlrev_b32_e32 v3, 16, v17
	v_lshlrev_b32_e32 v2, 16, v11
	v_pk_fma_f32 v[0:1], v[2:3], v[2:3], v[0:1]
	v_and_b32_e32 v3, 0xffff0000, v17
	v_and_b32_e32 v2, 0xffff0000, v11
	v_pk_fma_f32 v[0:1], v[2:3], v[2:3], v[0:1]
	s_nop 0
	v_pk_add_f32 v[122:123], v[122:123], v[0:1]
	s_cbranch_scc1 .LBB0_760
	v_and_b32_e32 v1, 64, v191
	v_xor_b32_e32 v0, 1, v191
	v_add_u32_e32 v2, 64, v1
	v_cmp_lt_i32_e32 vcc, v0, v2
	v_xor_b32_e32 v1, 2, v191
	v_xor_b32_e32 v5, 4, v191
	v_cndmask_b32_e32 v0, v191, v0, vcc
	v_lshlrev_b32_e32 v0, 2, v0
	ds_bpermute_b32 v3, v0, v125
	v_cmp_lt_i32_e32 vcc, v1, v2
	s_waitcnt lgkmcnt(0)
	v_add_f32_e32 v3, v125, v3
	v_cndmask_b32_e32 v1, v191, v1, vcc
	v_lshlrev_b32_e32 v1, 2, v1
	ds_bpermute_b32 v4, v1, v3
	v_cmp_lt_i32_e32 vcc, v5, v2
	s_waitcnt lgkmcnt(0)
	v_add_f32_e32 v3, v3, v4
	v_cndmask_b32_e32 v2, v191, v5, vcc
	v_lshlrev_b32_e32 v2, 2, v2
	ds_bpermute_b32 v4, v2, v3
	s_and_saveexec_b64 s[4:5], s[38:39]
	s_cbranch_execz .LBB0_753
	s_waitcnt lgkmcnt(0)
	v_add_f32_e32 v3, v3, v4
	v_fmamk_f32 v3, v3, 0x3b800000, v187
	v_mul_f32_e32 v4, 0x4b800000, v3
	v_cmp_gt_f32_e32 vcc, s33, v3
	s_nop 1
	v_cndmask_b32_e32 v3, v3, v4, vcc
	v_rsq_f32_e32 v3, v3
	s_nop 0
	v_mul_f32_e32 v4, 0x45800000, v3
	v_cndmask_b32_e32 v3, v3, v4, vcc
	ds_write_b32 v142, v3

; __device__ __forceinline__ void rem_tile(int pos, int& mt, int& nt) { if (pos < 65) { mt = pos; nt = 40; } else { mt = 64; nt = pos - 65; } }
;     ...
;     auto issue = [&](u32x4 (&ra)[4], u32x4 (&rb)[2], u32x4& rx) {
;       const int idc = l_id < last_id ? l_id : last_id;
;       int mt, nt; if (TMAP == 1) rem_tile(idc, mt, nt); else tile_of(idc, ntn, mt, nt);
;       const bf16_t* A = (l_kt < ktsplit) ? A0 : A1;
;       const int kk = (l_kt < ktsplit) ? l_kt : l_kt - ktsplit;
;       const int arow = mt * 2 * BMH + hh * BMH + srow;
;     ...
;     auto compute = [&](int buf) {
;       const unsigned char* Ab = As + buf * ASTG + (wn * 64 + lr) * 128;
;       const unsigned char* Ax = Ax0 + buf * 128;
;       const unsigned char* Bb = Bs + buf * 16384 + (wm * 64 + lr) * 128;
; #pragma unroll
;       for (int ks = 0; ks < 2; ++ks) {
;         if (TI == 5 && ks == 1) __builtin_amdgcn_sched_barrier(0);
;         const int sw = ((ks * 4 + lq) ^ (lr & 7)) << 4;
;         bf16x8 wf[4], xf[TI];
; #pragma unroll
;         for (int i = 0; i < 4; ++i) {
;           wf[i] = *(const bf16x8*)(Bb + i * 2048 + sw);
;           xf[i] = *(const bf16x8*)(Ab + i * 2048 + sw);
;         }
.LBB0_760:
	s_add_i32 s11, s6, 1
	s_cmp_eq_u32 s11, 4
	s_cselect_b64 s[4:5], -1, 0
	s_and_b64 s[36:37], s[4:5], exec
	s_load_dwordx2 s[36:37], s[0:1], 0x110
	s_waitcnt lgkmcnt(0)
	s_barrier
	ds_read_b128 v[0:3], v121 offset:49152
	ds_read_b128 v[4:7], v126 offset:16384
	ds_read_b128 v[8:11], v121 offset:51200
	ds_read_b128 v[14:17], v126 offset:18432
	s_cselect_b32 s8, s36, 0
	s_add_i32 s8, s8, s7
	s_min_i32 s36, s8, s13
	s_cmpk_gt_i32 s36, 0x3ff
	s_mov_b64 s[6:7], -1
	s_cbranch_scc0 .LBB0_762
	s_add_i32 s10, s36, 0xfffffc00
	s_mov_b64 s[6:7], 0

; #define MFMA16(a, b, c) __builtin_amdgcn_mfma_f32_16x16x32_bf16((a), (b), (c), 0, 0, 0)
;     ...
;     auto issue = [&](u32x4 (&ra)[4], u32x4 (&rb)[2], u32x4& rx) {
;       const int idc = l_id < last_id ? l_id : last_id;
;       int mt, nt; if (TMAP == 1) rem_tile(idc, mt, nt); else tile_of(idc, ntn, mt, nt);
;       const bf16_t* A = (l_kt < ktsplit) ? A0 : A1;
;       const int kk = (l_kt < ktsplit) ? l_kt : l_kt - ktsplit;
;       const int arow = mt * 2 * BMH + hh * BMH + srow;
;       const bf16_t* akb = A + kk * kstride + (tid & 7) * 8;
;       const bf16_t* wp = W + (size_t)(nt * 128 + wrow) * K + l_kt * 64 + (tid5 & 7) * 8;
; #pragma unroll
;       for (int i = 0; i < 4; ++i) {
;         int r = arow + 32 * i; r = r < M_ ? r : M_ - 1;
;         ra[i] = *(const u32x4*)(akb + (size_t)r * lda);
;       }
; #pragma unroll
;       for (int i = 0; i < 2; ++i) rb[i] = *(const u32x4*)(wp + (size_t)i * 64 * K);
;       if (TI == 5) rx = *(const u32x4*)(akb + (size_t)(arow - srow + 128) * lda);
;       if (++l_kt == nk) { l_kt = 0; l_id += G; }
;     };
;     ...
;     auto compute = [&](int buf) {
;       const unsigned char* Ab = As + buf * ASTG + (wn * 64 + lr) * 128;
;       const unsigned char* Ax = Ax0 + buf * 128;
;       const unsigned char* Bb = Bs + buf * 16384 + (wm * 64 + lr) * 128;
; #pragma unroll
;       for (int ks = 0; ks < 2; ++ks) {
;         if (TI == 5 && ks == 1) __builtin_amdgcn_sched_barrier(0);
;         const int sw = ((ks * 4 + lq) ^ (lr & 7)) << 4;
;         bf16x8 wf[4], xf[TI];
; #pragma unroll
;         for (int i = 0; i < 4; ++i) {
;           wf[i] = *(const bf16x8*)(Bb + i * 2048 + sw);
;           xf[i] = *(const bf16x8*)(Ab + i * 2048 + sw);
;         }
;         if (TI == 5) xf[TI - 1] = *(const bf16x8*)(Ax + ((ks * 4 + lq) << 4));
; #pragma unroll
;         for (int ni = 0; ni < 4; ++ni)
; #pragma unroll
;           for (int ti = 0; ti < 4; ++ti) acc[ni][ti] = MFMA16(wf[ni], xf[ti], acc[ni][ti]);
;         if (TI == 5) {
;           if (wn == 0) { acc[0][TI - 1] = MFMA16(wf[0], xf[TI - 1], acc[0][TI - 1]); acc[1][TI - 1] = MFMA16(wf[1], xf[TI - 1], acc[1][TI - 1]); }
;           else { acc[2][TI - 1] = MFMA16(wf[2], xf[TI - 1], acc[2][TI - 1]); acc[3][TI - 1] = MFMA16(wf[3], xf[TI - 1], acc[3][TI - 1]); }
;         }
;       }
;     };
.LBB0_764:
	s_and_b64 s[4:5], s[4:5], exec
	s_cselect_b32 s6, 0, s11
	s_waitcnt lgkmcnt(2)
	v_mfma_f32_16x16x32_bf16 v[18:21], v[0:3], v[4:7], v[50:53]
	s_cmp_lt_i32 s6, 2.0
	s_cselect_b32 s11, s43, 0
	s_cselect_b32 s36, s42, 0
	s_waitcnt lgkmcnt(0)
	v_mfma_f32_16x16x32_bf16 v[22:25], v[0:3], v[14:17], v[54:57]
	ds_read_b128 v[50:53], v126 offset:20480
	s_nop 1
	ds_read_b128 v[54:57], v126 offset:22528
	s_lshl_b32 s4, s6, 6
	v_add_u32_e32 v117, s7, v135
	s_waitcnt lgkmcnt(1)
	v_mfma_f32_16x16x32_bf16 v[58:61], v[0:3], v[50:53], v[58:61]
	s_ashr_i32 s5, s4, 31
	s_lshl_b64 s[4:5], s[4:5], 1
	s_add_u32 s36, s36, s4
	s_waitcnt lgkmcnt(0)
	v_mfma_f32_16x16x32_bf16 v[0:3], v[0:3], v[54:57], v[62:65]
	s_addc_u32 s37, s11, s5
	v_mov_b32_e32 v115, v12
	s_movk_i32 s3, 0x4000
	v_mfma_f32_16x16x32_bf16 v[62:65], v[8:11], v[4:7], v[66:69]
	v_lshl_add_u32 v126, s10, 7, v134
	s_mov_b32 s7, 0xc000
	s_add_i32 s35, s35, 2
	v_mfma_f32_16x16x32_bf16 v[66:69], v[8:11], v[14:17], v[70:73]
	s_cmp_lg_u32 s35, 4
	v_mfma_f32_16x16x32_bf16 v[74:77], v[8:11], v[50:53], v[74:77]
	v_mfma_f32_16x16x32_bf16 v[8:11], v[8:11], v[54:57], v[78:81]
	ds_read_b128 v[70:73], v121 offset:53248
	s_nop 1
	ds_read_b128 v[78:81], v121 offset:55296
	ds_read_b128 v[158:161], v127 offset:16384
	s_waitcnt lgkmcnt(2)
	v_mfma_f32_16x16x32_bf16 v[82:85], v[70:73], v[4:7], v[82:85]
	s_waitcnt lgkmcnt(1)
	v_mfma_f32_16x16x32_bf16 v[150:153], v[78:81], v[4:7], v[102:105]
	ds_read_b128 v[4:7], v13 offset:49152
	v_mfma_f32_16x16x32_bf16 v[128:131], v[70:73], v[14:17], v[86:89]
	v_mfma_f32_16x16x32_bf16 v[154:157], v[78:81], v[14:17], v[106:109]
	ds_read_b128 v[14:17], v13 offset:51200
	ds_read_b128 v[176:179], v127 offset:18432
	ds_read_b128 v[180:183], v127 offset:22528
	s_waitcnt lgkmcnt(1)
	v_mfma_f32_16x16x32_bf16 v[102:105], v[4:7], v[176:179], v[22:25]
	s_nop 2
	v_min_i32_e32 v22, 0x407f, v117
	v_ashrrev_i32_e32 v23, 31, v22
	v_mfma_f32_16x16x32_bf16 v[90:93], v[70:73], v[50:53], v[90:93]
	v_mfma_f32_16x16x32_bf16 v[146:149], v[70:73], v[54:57], v[110:113]
	s_waitcnt lgkmcnt(0)
	v_mfma_f32_16x16x32_bf16 v[70:73], v[4:7], v[180:183], v[0:3]
	s_nop 2
	v_min_i32_e32 v2, 0x405f, v117
	v_mfma_f32_16x16x32_bf16 v[110:113], v[4:7], v[158:161], v[18:21]
	v_lshlrev_b64 v[0:1], 9, v[22:23]
	v_ashrrev_i32_e32 v3, 31, v2
	ds_read_b128 v[22:25], v13 offset:53248
	ds_read_b128 v[18:21], v127 offset:20480
	v_mfma_f32_16x16x32_bf16 v[168:171], v[78:81], v[54:57], v[98:101]
	v_lshl_add_u64 v[54:55], s[36:37], 0, v[114:115]
	v_lshlrev_b64 v[2:3], 9, v[2:3]
	v_lshl_add_u64 v[2:3], v[54:55], 0, v[2:3]
	v_add_co_u32_e32 v2, vcc, s3, v2
	v_lshl_add_u64 v[0:1], v[54:55], 0, v[0:1]
	s_nop 0
	v_addc_co_u32_e32 v3, vcc, 0, v3, vcc
	s_waitcnt lgkmcnt(0)
	v_mfma_f32_16x16x32_bf16 v[86:89], v[4:7], v[18:21], v[58:61]
	global_load_dwordx4 v[4:7], v[0:1], off
	s_nop 0
	global_load_dwordx4 v[0:3], v[2:3], off
	v_min_i32_e32 v56, 0x403f, v117
	ds_read_b128 v[202:205], v13 offset:55296
	v_mfma_f32_16x16x32_bf16 v[106:109], v[14:17], v[158:161], v[62:65]
	v_ashrrev_i32_e32 v57, 31, v56
	v_ashrrev_i32_e32 v127, 31, v126
	s_mov_b32 s3, 0x8000
	v_mfma_f32_16x16x32_bf16 v[62:65], v[14:17], v[180:183], v[8:11]
	s_nop 2
	v_min_i32_e32 v10, 0x401f, v117
	v_lshlrev_b64 v[8:9], 9, v[56:57]
	v_ashrrev_i32_e32 v11, 31, v10
	v_lshl_add_u64 v[8:9], v[54:55], 0, v[8:9]
	v_lshlrev_b64 v[10:11], 9, v[10:11]
	v_mfma_f32_16x16x32_bf16 v[50:53], v[78:81], v[50:53], v[94:97]
	v_add_co_u32_e32 v8, vcc, s3, v8
	v_lshl_add_u64 v[10:11], v[54:55], 0, v[10:11]
	v_mfma_f32_16x16x32_bf16 v[94:97], v[14:17], v[176:179], v[66:69]
	v_addc_co_u32_e32 v9, vcc, 0, v9, vcc
	v_add_co_u32_e32 v10, vcc, s7, v10
	v_mfma_f32_16x16x32_bf16 v[98:101], v[22:25], v[158:161], v[82:85]
	v_mov_b32_e32 v117, v12
	v_addc_co_u32_e32 v11, vcc, 0, v11, vcc
	v_mfma_f32_16x16x32_bf16 v[82:85], v[22:25], v[176:179], v[128:131]
	v_mfma_f32_16x16x32_bf16 v[66:69], v[22:25], v[18:21], v[90:93]
	v_mfma_f32_16x16x32_bf16 v[54:57], v[22:25], v[180:183], v[146:149]
	v_lshlrev_b64 v[22:23], 9, v[126:127]
	v_lshl_add_u64 v[22:23], s[44:45], 0, v[22:23]
	v_lshl_add_u64 v[22:23], v[22:23], 0, s[4:5]
	v_lshl_add_u64 v[22:23], v[22:23], 0, v[116:117]
	v_add_co_u32_e32 v126, vcc, s3, v22
	v_mfma_f32_16x16x32_bf16 v[78:81], v[14:17], v[18:21], v[74:77]
	global_load_dwordx4 v[14:17], v[8:9], off
	s_nop 0
	global_load_dwordx4 v[8:11], v[10:11], off
	v_addc_co_u32_e32 v127, vcc, 0, v23, vcc
	s_waitcnt lgkmcnt(0)
	v_mfma_f32_16x16x32_bf16 v[58:61], v[202:205], v[18:21], v[50:53]
	global_load_dwordx4 v[22:25], v[22:23], off
	s_nop 0
	global_load_dwordx4 v[18:21], v[126:127], off
	v_mfma_f32_16x16x32_bf16 v[90:93], v[202:205], v[158:161], v[150:153]
	v_mfma_f32_16x16x32_bf16 v[74:77], v[202:205], v[176:179], v[154:157]
	v_mfma_f32_16x16x32_bf16 v[50:53], v[202:205], v[180:183], v[168:171]
	s_cbranch_scc1 .LBB0_776
	ds_read2_b32 v[128:129], v144 offset1:16
	ds_read2_b32 v[126:127], v144 offset0:32 offset1:48
	s_cmpk_gt_i32 s12, 0x3ff
	s_mov_b64 s[4:5], -1
	s_cbranch_scc0 .LBB0_768
	s_add_i32 s7, s12, 0xfffffc00
	s_movk_i32 s4, 0x4000
	s_cbranch_execz .LBB0_769

; __device__ __forceinline__ void rem_tile(int pos, int& mt, int& nt) { if (pos < 65) { mt = pos; nt = 40; } else { mt = 64; nt = pos - 65; } }
;     ...
;     auto issue = [&](u32x4 (&ra)[4], u32x4 (&rb)[2], u32x4& rx) {
;       const int idc = l_id < last_id ? l_id : last_id;
;       int mt, nt; if (TMAP == 1) rem_tile(idc, mt, nt); else tile_of(idc, ntn, mt, nt);
;       const bf16_t* A = (l_kt < ktsplit) ? A0 : A1;
;       const int kk = (l_kt < ktsplit) ? l_kt : l_kt - ktsplit;
;       const int arow = mt * 2 * BMH + hh * BMH + srow;
;     ...
;     auto compute = [&](int buf) {
;       const unsigned char* Ab = As + buf * ASTG + (wn * 64 + lr) * 128;
;       const unsigned char* Ax = Ax0 + buf * 128;
;       const unsigned char* Bb = Bs + buf * 16384 + (wm * 64 + lr) * 128;
; #pragma unroll
;       for (int ks = 0; ks < 2; ++ks) {
;         if (TI == 5 && ks == 1) __builtin_amdgcn_sched_barrier(0);
;         const int sw = ((ks * 4 + lq) ^ (lr & 7)) << 4;
;         bf16x8 wf[4], xf[TI];
; #pragma unroll
;         for (int i = 0; i < 4; ++i) {
;           wf[i] = *(const bf16x8*)(Bb + i * 2048 + sw);
;           xf[i] = *(const bf16x8*)(Ab + i * 2048 + sw);
;         }
;         if (TI == 5) xf[TI - 1] = *(const bf16x8*)(Ax + ((ks * 4 + lq) << 4));
.LBB0_939:
	v_add_u32_e32 v13, v180, v181
	ds_read_b128 v[148:151], v13 offset:32768
	v_add_u32_e32 v15, v179, v181
	s_waitcnt vmcnt(8)
	ds_read_b128 v[56:59], v15
	ds_read_b128 v[152:155], v13 offset:34816
	ds_read_b128 v[160:163], v15 offset:2048
	ds_read_b128 v[204:207], v15 offset:4096
	ds_read_b128 v[208:211], v15 offset:6144
	s_min_i32 s10, s7, s13
	s_cmpk_gt_i32 s10, 0x1ff
	s_mov_b64 s[4:5], -1
	s_cbranch_scc0 .LBB0_941
	s_add_i32 s9, s10, 0xfffffe00
	s_mov_b64 s[4:5], 0

; #define MFMA16(a, b, c) __builtin_amdgcn_mfma_f32_16x16x32_bf16((a), (b), (c), 0, 0, 0)
;     ...
;     auto issue = [&](u32x4 (&ra)[4], u32x4 (&rb)[2], u32x4& rx) {
;       const int idc = l_id < last_id ? l_id : last_id;
;       int mt, nt; if (TMAP == 1) rem_tile(idc, mt, nt); else tile_of(idc, ntn, mt, nt);
;       const bf16_t* A = (l_kt < ktsplit) ? A0 : A1;
;       const int kk = (l_kt < ktsplit) ? l_kt : l_kt - ktsplit;
;       const int arow = mt * 2 * BMH + hh * BMH + srow;
;       const bf16_t* akb = A + kk * kstride + (tid & 7) * 8;
;       const bf16_t* wp = W + (size_t)(nt * 128 + wrow) * K + l_kt * 64 + (tid5 & 7) * 8;
; #pragma unroll
;       for (int i = 0; i < 4; ++i) {
;         int r = arow + 32 * i; r = r < M_ ? r : M_ - 1;
;         ra[i] = *(const u32x4*)(akb + (size_t)r * lda);
;       }
; #pragma unroll
;       for (int i = 0; i < 2; ++i) rb[i] = *(const u32x4*)(wp + (size_t)i * 64 * K);
;       if (TI == 5) rx = *(const u32x4*)(akb + (size_t)(arow - srow + 128) * lda);
;       if (++l_kt == nk) { l_kt = 0; l_id += G; }
;     };
;     ...
;     auto compute = [&](int buf) {
;       const unsigned char* Ab = As + buf * ASTG + (wn * 64 + lr) * 128;
;       const unsigned char* Ax = Ax0 + buf * 128;
;       const unsigned char* Bb = Bs + buf * 16384 + (wm * 64 + lr) * 128;
; #pragma unroll
;       for (int ks = 0; ks < 2; ++ks) {
;         if (TI == 5 && ks == 1) __builtin_amdgcn_sched_barrier(0);
;         const int sw = ((ks * 4 + lq) ^ (lr & 7)) << 4;
;         bf16x8 wf[4], xf[TI];
; #pragma unroll
;         for (int i = 0; i < 4; ++i) {
;           wf[i] = *(const bf16x8*)(Bb + i * 2048 + sw);
;           xf[i] = *(const bf16x8*)(Ab + i * 2048 + sw);
;         }
;         if (TI == 5) xf[TI - 1] = *(const bf16x8*)(Ax + ((ks * 4 + lq) << 4));
; #pragma unroll
;         for (int ni = 0; ni < 4; ++ni)
; #pragma unroll
;           for (int ti = 0; ti < 4; ++ti) acc[ni][ti] = MFMA16(wf[ni], xf[ti], acc[ni][ti]);
;         if (TI == 5) {
;           if (wn == 0) { acc[0][TI - 1] = MFMA16(wf[0], xf[TI - 1], acc[0][TI - 1]); acc[1][TI - 1] = MFMA16(wf[1], xf[TI - 1], acc[1][TI - 1]); }
;           else { acc[2][TI - 1] = MFMA16(wf[2], xf[TI - 1], acc[2][TI - 1]); acc[3][TI - 1] = MFMA16(wf[3], xf[TI - 1], acc[3][TI - 1]); }
;         }
;       }
;     };
.LBB0_943:
	s_cmp_lt_i32 s6, 2.0
	v_add_u32_e32 v14, s4, v176
	s_mul_i32 s4, s6, 0x60
	s_cselect_b32 s10, s47, 0
	s_cselect_b32 s11, s46, 0
	s_ashr_i32 s5, s4, 31
	s_lshl_b64 s[4:5], s[4:5], 1
	s_add_u32 s4, s11, s4
	s_addc_u32 s5, s10, s5
	v_mov_b32_e32 v169, v12
	v_min_i32_e32 v42, 0x405f, v14
	v_lshl_add_u64 v[212:213], s[4:5], 0, v[168:169]
	v_min_i32_e32 v40, 0x407f, v14
	v_add_u32_e32 v42, 32, v42
	v_mad_i64_i32 v[40:41], s[10:11], v40, s83, v[212:213]
	v_mad_i64_i32 v[44:45], s[10:11], v42, s83, v[212:213]
	s_waitcnt lgkmcnt(1)
	v_mfma_f32_16x16x32_bf16 v[140:143], v[148:151], v[204:207], v[128:131]
	v_lshl_add_u32 v60, s9, 7, v174
	v_ashrrev_i32_e32 v61, 31, v60
	s_lshl_b32 s4, s6, 6
	ds_read_b128 v[128:131], v13 offset:36864
	global_load_dwordx4 v[40:43], v[40:41], off
	s_nop 0
	global_load_dwordx4 v[44:47], v[44:45], off
	ds_read_b128 v[156:159], v13 offset:38912
	v_lshlrev_b64 v[60:61], 11, v[60:61]
	s_ashr_i32 s5, s4, 31
	v_lshl_add_u64 v[60:61], s[50:51], 0, v[60:61]
	v_lshl_add_u64 v[60:61], s[4:5], 1, v[60:61]
	v_mov_b32_e32 v171, v12
	v_min_i32_e32 v48, 0x403f, v14
	v_min_i32_e32 v50, 0x401f, v14
	v_lshl_add_u64 v[60:61], v[60:61], 0, v[170:171]
	v_sub_u32_e32 v14, v14, v173
	v_add_u32_e32 v48, 64, v48
	v_add_u32_e32 v50, 0x60, v50
	v_add_co_u32_e32 v64, vcc, s2, v60
	v_add_u32_e32 v14, 0x80, v14
	v_mfma_f32_16x16x32_bf16 v[136:139], v[148:151], v[56:59], v[136:139]
	v_mad_i64_i32 v[48:49], s[10:11], v48, s83, v[212:213]
	v_mad_i64_i32 v[52:53], s[10:11], v50, s83, v[212:213]
	v_mfma_f32_16x16x32_bf16 v[120:123], v[152:155], v[56:59], v[120:123]
	v_addc_co_u32_e32 v65, vcc, 0, v61, vcc
	global_load_dwordx4 v[48:51], v[48:49], off
	s_nop 0
	global_load_dwordx4 v[52:55], v[52:53], off
	s_waitcnt lgkmcnt(1)
	v_mfma_f32_16x16x32_bf16 v[144:147], v[128:131], v[56:59], v[100:103]
	global_load_dwordx4 v[60:63], v[60:61], off
	s_nop 0
	global_load_dwordx4 v[64:67], v[64:65], off
	ds_read_b128 v[100:103], v185
	s_waitcnt lgkmcnt(1)
	v_mfma_f32_16x16x32_bf16 v[80:83], v[156:159], v[56:59], v[80:83]
	v_mad_i64_i32 v[56:57], s[4:5], v14, s83, v[212:213]
	global_load_dwordx4 v[56:59], v[56:57], off
	s_sub_u32 s101, s8, 0
	s_lshr_b32 s101, s101, 1
	s_lshl_b32 s101, s101, 14
	s_add_u32 s101, s101, s100
	v_add_u32_e32 v250, s101, v251
	s_sub_u32 s101, s8, 0
	s_cmp_le_u32 s101, 14
	s_cselect_b32 s101, -1, 0
	v_and_b32_e32 v250, s101, v250
	global_load_dword v249, v250, s[44:45]
	v_mfma_f32_16x16x32_bf16 v[132:135], v[148:151], v[160:163], v[132:135]
	v_mfma_f32_16x16x32_bf16 v[124:127], v[148:151], v[208:211], v[124:127]
	v_mfma_f32_16x16x32_bf16 v[116:119], v[152:155], v[160:163], v[116:119]
	v_mfma_f32_16x16x32_bf16 v[112:115], v[152:155], v[204:207], v[112:115]
	v_mfma_f32_16x16x32_bf16 v[104:107], v[152:155], v[208:211], v[104:107]
	v_mfma_f32_16x16x32_bf16 v[96:99], v[128:131], v[160:163], v[96:99]
	v_mfma_f32_16x16x32_bf16 v[92:95], v[128:131], v[204:207], v[92:95]
	v_mfma_f32_16x16x32_bf16 v[84:87], v[128:131], v[208:211], v[84:87]
	v_mfma_f32_16x16x32_bf16 v[76:79], v[156:159], v[160:163], v[76:79]
	v_mfma_f32_16x16x32_bf16 v[72:75], v[156:159], v[204:207], v[72:75]
	v_mfma_f32_16x16x32_bf16 v[68:71], v[156:159], v[208:211], v[68:71]
	s_and_saveexec_b64 s[4:5], s[40:41]
	s_xor_b64 s[4:5], exec, s[4:5]
	s_cbranch_execz .LBB0_945
	s_waitcnt lgkmcnt(0)
	v_mfma_f32_16x16x32_bf16 v[36:39], v[128:131], v[100:103], v[36:39]
	v_mfma_f32_16x16x32_bf16 v[32:35], v[156:159], v[100:103], v[32:35]

; __device__ __forceinline__ void rem_tile(int pos, int& mt, int& nt) { if (pos < 65) { mt = pos; nt = 40; } else { mt = 64; nt = pos - 65; } }
;     ...
;     auto issue = [&](u32x4 (&ra)[4], u32x4 (&rb)[2], u32x4& rx) {
;       const int idc = l_id < last_id ? l_id : last_id;
;       int mt, nt; if (TMAP == 1) rem_tile(idc, mt, nt); else tile_of(idc, ntn, mt, nt);
;       const bf16_t* A = (l_kt < ktsplit) ? A0 : A1;
;       const int kk = (l_kt < ktsplit) ? l_kt : l_kt - ktsplit;
;       const int arow = mt * 2 * BMH + hh * BMH + srow;
;     ...
; #pragma unroll 1
;     for (int s = 0; s < S; s += 2) {
;       issue(ra0, rb0, rx0);
;       compute(0);
;       store(ra1, rb1, rx1, 1);
;       __syncthreads();
;       issue(ra1, rb1, rx1);
.LBB0_953:
	s_or_b64 exec, exec, s[4:5]
	s_add_i32 s10, s6, 1
	s_cmp_eq_u32 s10, 16
	s_cselect_b64 s[4:5], -1, 0
	s_and_b64 s[34:35], s[4:5], exec
	s_load_dwordx2 s[34:35], s[0:1], 0x110
	s_waitcnt lgkmcnt(0)
	s_barrier
	ds_read_b128 v[148:151], v13 offset:49152
	ds_read_b128 v[20:23], v15 offset:16384
	ds_read_b128 v[152:155], v13 offset:51200
	s_waitcnt vmcnt(8)
	ds_read_b128 v[28:31], v15 offset:18432
	ds_read_b128 v[160:163], v15 offset:20480
	ds_read_b128 v[204:207], v15 offset:22528
	s_cselect_b32 s56, s34, 0
	s_add_i32 s56, s56, s7
	s_min_i32 s11, s56, s13
	s_cmpk_gt_i32 s11, 0x1ff
	s_mov_b64 s[6:7], -1
	s_cbranch_scc0 .LBB0_955
	s_add_i32 s9, s11, 0xfffffe00
	s_mov_b64 s[6:7], 0

; #define MFMA16(a, b, c) __builtin_amdgcn_mfma_f32_16x16x32_bf16((a), (b), (c), 0, 0, 0)
;     ...
;     auto issue = [&](u32x4 (&ra)[4], u32x4 (&rb)[2], u32x4& rx) {
;       const int idc = l_id < last_id ? l_id : last_id;
;       int mt, nt; if (TMAP == 1) rem_tile(idc, mt, nt); else tile_of(idc, ntn, mt, nt);
;       const bf16_t* A = (l_kt < ktsplit) ? A0 : A1;
;       const int kk = (l_kt < ktsplit) ? l_kt : l_kt - ktsplit;
;       const int arow = mt * 2 * BMH + hh * BMH + srow;
;       const bf16_t* akb = A + kk * kstride + (tid & 7) * 8;
;       const bf16_t* wp = W + (size_t)(nt * 128 + wrow) * K + l_kt * 64 + (tid5 & 7) * 8;
; #pragma unroll
;       for (int i = 0; i < 4; ++i) {
;         int r = arow + 32 * i; r = r < M_ ? r : M_ - 1;
;         ra[i] = *(const u32x4*)(akb + (size_t)r * lda);
;       }
; #pragma unroll
;       for (int i = 0; i < 2; ++i) rb[i] = *(const u32x4*)(wp + (size_t)i * 64 * K);
;       if (TI == 5) rx = *(const u32x4*)(akb + (size_t)(arow - srow + 128) * lda);
;       if (++l_kt == nk) { l_kt = 0; l_id += G; }
;     };
;     ...
;     auto compute = [&](int buf) {
;       const unsigned char* Ab = As + buf * ASTG + (wn * 64 + lr) * 128;
;       const unsigned char* Ax = Ax0 + buf * 128;
;       const unsigned char* Bb = Bs + buf * 16384 + (wm * 64 + lr) * 128;
; #pragma unroll
;       for (int ks = 0; ks < 2; ++ks) {
;         if (TI == 5 && ks == 1) __builtin_amdgcn_sched_barrier(0);
;         const int sw = ((ks * 4 + lq) ^ (lr & 7)) << 4;
;         bf16x8 wf[4], xf[TI];
; #pragma unroll
;         for (int i = 0; i < 4; ++i) {
;           wf[i] = *(const bf16x8*)(Bb + i * 2048 + sw);
;           xf[i] = *(const bf16x8*)(Ab + i * 2048 + sw);
;         }
;         if (TI == 5) xf[TI - 1] = *(const bf16x8*)(Ax + ((ks * 4 + lq) << 4));
; #pragma unroll
;         for (int ni = 0; ni < 4; ++ni)
; #pragma unroll
;           for (int ti = 0; ti < 4; ++ti) acc[ni][ti] = MFMA16(wf[ni], xf[ti], acc[ni][ti]);
;         if (TI == 5) {
;           if (wn == 0) { acc[0][TI - 1] = MFMA16(wf[0], xf[TI - 1], acc[0][TI - 1]); acc[1][TI - 1] = MFMA16(wf[1], xf[TI - 1], acc[1][TI - 1]); }
;           else { acc[2][TI - 1] = MFMA16(wf[2], xf[TI - 1], acc[2][TI - 1]); acc[3][TI - 1] = MFMA16(wf[3], xf[TI - 1], acc[3][TI - 1]); }
;         }
;       }
;     };
.LBB0_957:
	s_and_b64 s[4:5], s[4:5], exec
	s_cselect_b32 s57, 0, s10
	s_cmp_lt_i32 s57, 2.0
	s_mul_i32 s4, s57, 0x60
	s_cselect_b32 s7, s47, 0
	s_cselect_b32 s10, s46, 0
	s_ashr_i32 s5, s4, 31
	s_lshl_b64 s[4:5], s[4:5], 1
	v_add_u32_e32 v210, s6, v176
	s_add_u32 s4, s10, s4
	s_addc_u32 s5, s7, s5
	v_mov_b32_e32 v169, v12
	v_min_i32_e32 v2, 0x405f, v210
	v_lshl_add_u64 v[208:209], s[4:5], 0, v[168:169]
	v_min_i32_e32 v0, 0x407f, v210
	v_add_u32_e32 v2, 32, v2
	v_mad_i64_i32 v[0:1], s[6:7], v0, s83, v[208:209]
	v_mad_i64_i32 v[4:5], s[6:7], v2, s83, v[208:209]
	s_waitcnt lgkmcnt(1)
	v_mfma_f32_16x16x32_bf16 v[140:143], v[148:151], v[160:163], v[132:135]
	v_lshl_add_u32 v24, s9, 7, v174
	v_ashrrev_i32_e32 v25, 31, v24
	s_lshl_b32 s4, s57, 6
	ds_read_b128 v[132:135], v13 offset:53248
	global_load_dwordx4 v[0:3], v[0:1], off
	s_nop 0
	global_load_dwordx4 v[4:7], v[4:5], off
	ds_read_b128 v[156:159], v13 offset:55296
	v_lshlrev_b64 v[24:25], 11, v[24:25]
	s_ashr_i32 s5, s4, 31
	v_lshl_add_u64 v[24:25], s[50:51], 0, v[24:25]
	v_lshl_add_u64 v[24:25], s[4:5], 1, v[24:25]
	v_mov_b32_e32 v171, v12
	v_min_i32_e32 v8, 0x403f, v210
	v_min_i32_e32 v10, 0x401f, v210
	v_lshl_add_u64 v[24:25], v[24:25], 0, v[170:171]
	v_sub_u32_e32 v13, v210, v173
	v_add_u32_e32 v8, 64, v8
	v_add_u32_e32 v10, 0x60, v10
	v_add_co_u32_e32 v26, vcc, s2, v24
	v_add_u32_e32 v13, 0x80, v13
	v_mfma_f32_16x16x32_bf16 v[128:131], v[148:151], v[28:31], v[128:131]
	v_mad_i64_i32 v[8:9], s[6:7], v8, s83, v[208:209]
	v_mad_i64_i32 v[16:17], s[6:7], v10, s83, v[208:209]
	v_mfma_f32_16x16x32_bf16 v[116:119], v[152:155], v[28:31], v[116:119]
	v_addc_co_u32_e32 v27, vcc, 0, v25, vcc
	global_load_dwordx4 v[8:11], v[8:9], off
	s_nop 0
	global_load_dwordx4 v[16:19], v[16:17], off
	s_waitcnt lgkmcnt(1)
	v_mfma_f32_16x16x32_bf16 v[96:99], v[132:135], v[28:31], v[96:99]
	s_waitcnt lgkmcnt(0)
	v_mfma_f32_16x16x32_bf16 v[76:79], v[156:159], v[28:31], v[76:79]
	v_mad_i64_i32 v[28:29], s[4:5], v13, s83, v[208:209]
	v_mfma_f32_16x16x32_bf16 v[136:139], v[148:151], v[20:23], v[136:139]
	v_mfma_f32_16x16x32_bf16 v[120:123], v[152:155], v[20:23], v[120:123]
	v_mfma_f32_16x16x32_bf16 v[144:147], v[132:135], v[20:23], v[104:107]
	v_mfma_f32_16x16x32_bf16 v[80:83], v[156:159], v[20:23], v[80:83]
	global_load_dwordx4 v[20:23], v[24:25], off
	s_nop 0
	global_load_dwordx4 v[24:27], v[26:27], off
	ds_read_b128 v[104:107], v185 offset:128
	global_load_dwordx4 v[28:31], v[28:29], off
	s_sub_u32 s101, s8, 0
	s_lshr_b32 s101, s101, 1
	s_lshl_b32 s101, s101, 14
	s_add_u32 s101, s101, s100
	v_add_u32_e32 v250, s101, v251
	s_sub_u32 s101, s8, 0
	s_cmp_le_u32 s101, 14
	s_cselect_b32 s101, -1, 0
	v_and_b32_e32 v250, s101, v250
	global_load_dword v249, v250, s[52:53]
	v_mfma_f32_16x16x32_bf16 v[124:127], v[148:151], v[204:207], v[124:127]
	v_mfma_f32_16x16x32_bf16 v[112:115], v[152:155], v[160:163], v[112:115]
	v_mfma_f32_16x16x32_bf16 v[100:103], v[152:155], v[204:207], v[100:103]
	v_mfma_f32_16x16x32_bf16 v[92:95], v[132:135], v[160:163], v[92:95]
	v_mfma_f32_16x16x32_bf16 v[84:87], v[132:135], v[204:207], v[84:87]
	v_mfma_f32_16x16x32_bf16 v[72:75], v[156:159], v[160:163], v[72:75]
	v_mfma_f32_16x16x32_bf16 v[68:71], v[156:159], v[204:207], v[68:71]
	s_and_saveexec_b64 s[4:5], s[40:41]
	s_xor_b64 s[4:5], exec, s[4:5]
	s_cbranch_execz .LBB0_959
	s_waitcnt lgkmcnt(0)
	v_mfma_f32_16x16x32_bf16 v[36:39], v[132:135], v[104:107], v[36:39]
	v_mfma_f32_16x16x32_bf16 v[32:35], v[156:159], v[104:107], v[32:35]

; template <int EPI>
; __device__ __forceinline__ void gemm_wide(const WS& ws, const bf16_t* A, int lda, const bf16_t* __restrict__ W, int K, float invK,
;                                           int ntn, int ntiles, int bid) {
;     ...
;     auto issue = [&]() {
;       const int idc = l_id < last_id ? l_id : last_id;
;       int mt, nt; tile_of(idc, ntn, mt, nt);
;       const int arow = mt * 256 + hh * 128 + srow;
;       const bf16_t* akb = A + l_kt * 64 + (tid & 7) * 8;
;       const bf16_t* wp = W + (size_t)(nt * 256 + wrow) * K + l_kt * 64 + (tid5 & 7) * 8;
;     ...
;     auto compute = [&](int buf) {
;       const unsigned char* Ab = As + buf * 16384 + (wn * 64 + lr) * 128;
;       const unsigned char* Bb = Bs + buf * 32768 + (wm * 64 + lr) * 128;
; #pragma unroll
;       for (int ks = 0; ks < 2; ++ks) {
;         if (ks == 1) __builtin_amdgcn_sched_barrier(0);
;         const int sw = ((ks * 4 + lq) ^ (lr & 7)) << 4;
;         bf16x8 xf[4], wf[4];
; #pragma unroll
;         for (int i = 0; i < 4; ++i) { xf[i] = *(const bf16x8*)(Ab + i * 2048 + sw); wf[i] = *(const bf16x8*)(Bb + i * 2048 + sw); }
.LBB0_1039:
	s_and_b32 s5, s35, 1
	v_lshl_add_u32 v13, s5, 15, v206
	v_add_u32_e32 v134, v13, v207
	ds_read_b128 v[98:101], v134
	v_lshl_add_u32 v226, s5, 14, v205
	v_add_u32_e32 v118, v226, v207
	ds_read_b128 v[102:105], v118
	ds_read_b128 v[110:113], v118 offset:2048
	ds_read_b128 v[106:109], v134 offset:2048
	ds_read_b128 v[178:181], v118 offset:4096
	ds_read_b128 v[182:185], v118 offset:6144
	s_min_i32 s8, s66, s63
	s_cmpk_gt_i32 s8, 0x4ff
	s_mov_b64 s[4:5], -1
	s_cbranch_scc0 .LBB0_1041
	s_add_i32 s7, s8, 0xfffffb00
	s_mov_b64 s[4:5], 0

; #define MFMA16(a, b, c) __builtin_amdgcn_mfma_f32_16x16x32_bf16((a), (b), (c), 0, 0, 0)
; template <int EPI>
; __device__ __forceinline__ void gemm_wide(const WS& ws, const bf16_t* A, int lda, const bf16_t* __restrict__ W, int K, float invK,
;                                           int ntn, int ntiles, int bid) {
;     ...
;     auto issue = [&]() {
;       const int idc = l_id < last_id ? l_id : last_id;
;       int mt, nt; tile_of(idc, ntn, mt, nt);
;       const int arow = mt * 256 + hh * 128 + srow;
;       const bf16_t* akb = A + l_kt * 64 + (tid & 7) * 8;
;       const bf16_t* wp = W + (size_t)(nt * 256 + wrow) * K + l_kt * 64 + (tid5 & 7) * 8;
; #pragma unroll
;       for (int i = 0; i < 4; ++i) {
;         int r = arow + 32 * i; r = r < M_ ? r : M_ - 1;
;         ra[i] = *(const u32x4*)(akb + (size_t)r * lda);
;         rb[i] = *(const u32x4*)(wp + (size_t)i * 64 * K);
;       }
;     ...
;     auto compute = [&](int buf) {
;       const unsigned char* Ab = As + buf * 16384 + (wn * 64 + lr) * 128;
;       const unsigned char* Bb = Bs + buf * 32768 + (wm * 64 + lr) * 128;
; #pragma unroll
;       for (int ks = 0; ks < 2; ++ks) {
;         if (ks == 1) __builtin_amdgcn_sched_barrier(0);
;         const int sw = ((ks * 4 + lq) ^ (lr & 7)) << 4;
;         bf16x8 xf[4], wf[4];
; #pragma unroll
;         for (int i = 0; i < 4; ++i) { xf[i] = *(const bf16x8*)(Ab + i * 2048 + sw); wf[i] = *(const bf16x8*)(Bb + i * 2048 + sw); }
; #pragma unroll
;         for (int ni = 0; ni < 4; ++ni)
; #pragma unroll
;           for (int ti = 0; ti < 4; ++ti) accA[ni][ti] = MFMA16(wf[ni], xf[ti], accA[ni][ti]);
; #pragma unroll
;         for (int i = 0; i < 4; ++i) wf[i] = *(const bf16x8*)(Bb + 16384 + i * 2048 + sw);
; #pragma unroll
;         for (int ni = 0; ni < 4; ++ni)
; #pragma unroll
;           for (int ti = 0; ti < 4; ++ti) accB[ni][ti] = MFMA16(wf[ni], xf[ti], accB[ni][ti]);
;       }
;     };
.LBB0_1043:
	s_and_b32 s5, s35, 1
	s_waitcnt lgkmcnt(2)
	v_mfma_f32_16x16x32_bf16 v[142:145], v[106:109], v[102:105], v[142:145]
	v_lshl_add_u32 v118, s7, 8, v201
	v_add_u32_e32 v224, s4, v202
	s_lshl_b32 s4, s65, 6
	v_mfma_f32_16x16x32_bf16 v[158:161], v[98:101], v[102:105], v[158:161]
	v_ashrrev_i32_e32 v119, 31, v118
	s_ashr_i32 s5, s4, 31
	s_lshl_b64 s[4:5], s[4:5], 1
	v_mfma_f32_16x16x32_bf16 v[154:157], v[98:101], v[110:113], v[154:157]
	v_mov_b32_e32 v169, v12
	v_lshl_add_u64 v[220:221], v[162:163], 0, s[4:5]
	s_mov_b32 s3, 0x20000
	s_waitcnt lgkmcnt(1)
	v_mfma_f32_16x16x32_bf16 v[150:153], v[98:101], v[178:181], v[150:153]
	s_mov_b32 s2, 0x20000
	s_waitcnt lgkmcnt(0)
	v_mfma_f32_16x16x32_bf16 v[146:149], v[98:101], v[182:185], v[146:149]
	v_mfma_f32_16x16x32_bf16 v[138:141], v[106:109], v[110:113], v[138:141]
	v_mfma_f32_16x16x32_bf16 v[130:133], v[106:109], v[178:181], v[130:133]
	v_mfma_f32_16x16x32_bf16 v[114:117], v[106:109], v[182:185], v[114:117]
	ds_read_b128 v[98:101], v134 offset:4096
	ds_read_b128 v[106:109], v134 offset:6144
	ds_read_b128 v[122:125], v134 offset:18432
	s_waitcnt lgkmcnt(2)
	v_mfma_f32_16x16x32_bf16 v[94:97], v[98:101], v[102:105], v[94:97]
	v_mfma_f32_16x16x32_bf16 v[90:93], v[98:101], v[110:113], v[90:93]
	v_mfma_f32_16x16x32_bf16 v[86:89], v[98:101], v[178:181], v[86:89]
	v_mfma_f32_16x16x32_bf16 v[82:85], v[98:101], v[182:185], v[82:85]
	ds_read_b128 v[98:101], v134 offset:16384
	s_waitcnt lgkmcnt(2)
	v_mfma_f32_16x16x32_bf16 v[78:81], v[106:109], v[102:105], v[78:81]
	v_mfma_f32_16x16x32_bf16 v[74:77], v[106:109], v[110:113], v[74:77]
	v_mfma_f32_16x16x32_bf16 v[70:73], v[106:109], v[178:181], v[70:73]
	v_mfma_f32_16x16x32_bf16 v[66:69], v[106:109], v[182:185], v[66:69]
	v_lshlrev_b64 v[106:107], 11, v[118:119]
	v_lshl_add_u64 v[106:107], s[48:49], 0, v[106:107]
	v_lshl_add_u64 v[106:107], v[106:107], 0, s[4:5]
	v_min_i32_e32 v108, 0x405f, v224
	v_lshl_add_u64 v[222:223], v[106:107], 0, v[168:169]
	v_min_i32_e32 v106, 0x407f, v224
	v_ashrrev_i32_e32 v109, 31, v108
	s_waitcnt lgkmcnt(0)
	v_mfma_f32_16x16x32_bf16 v[62:65], v[98:101], v[102:105], v[62:65]
	v_ashrrev_i32_e32 v107, 31, v106
	v_lshlrev_b64 v[106:107], 11, v[106:107]
	v_lshl_add_u64 v[106:107], v[220:221], 0, v[106:107]
	v_mfma_f32_16x16x32_bf16 v[58:61], v[98:101], v[110:113], v[58:61]
	global_load_dwordx4 v[126:129], v[222:223], off
	v_mfma_f32_16x16x32_bf16 v[54:57], v[98:101], v[178:181], v[54:57]
	v_mfma_f32_16x16x32_bf16 v[50:53], v[98:101], v[182:185], v[50:53]
	v_lshlrev_b64 v[98:99], 11, v[108:109]
	v_lshl_add_u64 v[98:99], v[220:221], 0, v[98:99]
	v_add_co_u32_e32 v98, vcc, s82, v98
	v_mfma_f32_16x16x32_bf16 v[46:49], v[122:125], v[102:105], v[46:49]
	s_nop 0
	v_addc_co_u32_e32 v99, vcc, 0, v99, vcc
	global_load_dwordx4 v[118:121], v[106:107], off
	s_nop 0
	global_load_dwordx4 v[106:109], v[98:99], off
	ds_read_b128 v[212:215], v134 offset:20480
	ds_read_b128 v[216:219], v134 offset:22528
	v_add_co_u32_e32 v98, vcc, s3, v222
	v_mfma_f32_16x16x32_bf16 v[42:45], v[122:125], v[110:113], v[42:45]
	s_nop 0
	v_addc_co_u32_e32 v99, vcc, 0, v223, vcc
	v_mfma_f32_16x16x32_bf16 v[38:41], v[122:125], v[178:181], v[38:41]
	v_mfma_f32_16x16x32_bf16 v[34:37], v[122:125], v[182:185], v[34:37]
	global_load_dwordx4 v[122:125], v[98:99], off
	v_min_i32_e32 v98, 0x403f, v224
	v_ashrrev_i32_e32 v99, 31, v98
	v_lshlrev_b64 v[98:99], 11, v[98:99]
	v_lshl_add_u64 v[98:99], v[220:221], 0, v[98:99]
	v_add_co_u32_e32 v98, vcc, s3, v98
	v_min_i32_e32 v224, 0x401f, v224
	s_nop 0
	v_addc_co_u32_e32 v99, vcc, 0, v99, vcc
	s_mov_b32 s3, 0x40000
	v_ashrrev_i32_e32 v225, 31, v224
	s_waitcnt lgkmcnt(1)
	v_mfma_f32_16x16x32_bf16 v[30:33], v[212:215], v[102:105], v[30:33]
	v_add_co_u32_e32 v134, vcc, s3, v222
	s_mov_b32 s3, 0x30000
	v_mfma_f32_16x16x32_bf16 v[26:29], v[212:215], v[110:113], v[26:29]
	v_addc_co_u32_e32 v135, vcc, 0, v223, vcc
	global_load_dwordx4 v[98:101], v[98:99], off
	v_mfma_f32_16x16x32_bf16 v[22:25], v[212:215], v[178:181], v[22:25]
	global_load_dwordx4 v[134:137], v[134:135], off
	v_mfma_f32_16x16x32_bf16 v[18:21], v[212:215], v[182:185], v[18:21]
	v_lshlrev_b64 v[212:213], 11, v[224:225]
	v_lshl_add_u64 v[212:213], v[220:221], 0, v[212:213]
	s_waitcnt lgkmcnt(0)
	v_mfma_f32_16x16x32_bf16 v[14:17], v[216:219], v[102:105], v[14:17]
	v_add_co_u32_e32 v102, vcc, s3, v212
	s_mov_b32 s3, 0x60000
	s_nop 0
	v_addc_co_u32_e32 v103, vcc, 0, v213, vcc
	v_mfma_f32_16x16x32_bf16 v[8:11], v[216:219], v[110:113], v[8:11]
	v_add_co_u32_e32 v110, vcc, s3, v222
	global_load_dwordx4 v[102:105], v[102:103], off
	s_nop 0
	v_addc_co_u32_e32 v111, vcc, 0, v223, vcc
	global_load_dwordx4 v[110:113], v[110:111], off
	v_mfma_f32_16x16x32_bf16 v[4:7], v[216:219], v[178:181], v[4:7]
	v_mfma_f32_16x16x32_bf16 v[0:3], v[216:219], v[182:185], v[0:3]
	v_add_u32_e32 v13, v13, v208
	ds_read_b128 v[178:181], v13
	v_add_u32_e32 v169, v226, v208
	ds_read_b128 v[182:185], v169
	ds_read_b128 v[212:215], v169 offset:2048
	ds_read_b128 v[216:219], v169 offset:4096
	ds_read_b128 v[220:223], v169 offset:6144
	ds_read_b128 v[244:247], v13 offset:2048
	ds_read_b128 v[248:251], v13 offset:4096
	ds_read_b128 v[252:255], v13 offset:6144
	s_add_i32 s6, s6, 1
	s_waitcnt lgkmcnt(6)
	v_mfma_f32_16x16x32_bf16 v[158:161], v[178:181], v[182:185], v[158:161]
	s_waitcnt lgkmcnt(5)
	v_mfma_f32_16x16x32_bf16 v[154:157], v[178:181], v[212:215], v[154:157]
	s_waitcnt lgkmcnt(4)
	v_mfma_f32_16x16x32_bf16 v[150:153], v[178:181], v[216:219], v[150:153]
	s_waitcnt lgkmcnt(3)
; #define MFMA16(a, b, c) __builtin_amdgcn_mfma_f32_16x16x32_bf16((a), (b), (c), 0, 0, 0)
; template <int EPI>
; __device__ __forceinline__ void gemm_wide(const WS& ws, const bf16_t* A, int lda, const bf16_t* __restrict__ W, int K, float invK,
;                                           int ntn, int ntiles, int bid) {
;     ...
;     auto store = [&](int buf) {
; #pragma unroll
;       for (int i = 0; i < 4; ++i) {
;         ss[i] += sumsq8(__builtin_bit_cast(bf16x8, ra[i]));
;         *(u32x4*)(As + buf * 16384 + i * 4096 + soff) = ra[i];
;         *(u32x4*)(Bs + buf * 32768 + i * 8192 + woff) = rb[i];
;       }
;       if (++st_kt == nk) {
;         st_kt = 0;
; #pragma unroll
;         for (int i = 0; i < 4; ++i) {
;           float t = ss[i];
;           t += __shfl_xor(t, 1); t += __shfl_xor(t, 2); t += __shfl_xor(t, 4);
;           if ((tid & 7) == 0) rsl[srow + 32 * i] = rsqrtf(t * invK + EPS_);
;           ss[i] = 0.f;
;         }
;       }
;     };
;     auto compute = [&](int buf) {
;       const unsigned char* Ab = As + buf * 16384 + (wn * 64 + lr) * 128;
;       const unsigned char* Bb = Bs + buf * 32768 + (wm * 64 + lr) * 128;
; #pragma unroll
;       for (int ks = 0; ks < 2; ++ks) {
;         if (ks == 1) __builtin_amdgcn_sched_barrier(0);
;         const int sw = ((ks * 4 + lq) ^ (lr & 7)) << 4;
;         bf16x8 xf[4], wf[4];
; #pragma unroll
;         for (int i = 0; i < 4; ++i) { xf[i] = *(const bf16x8*)(Ab + i * 2048 + sw); wf[i] = *(const bf16x8*)(Bb + i * 2048 + sw); }
; #pragma unroll
;         for (int ni = 0; ni < 4; ++ni)
; #pragma unroll
;           for (int ti = 0; ti < 4; ++ti) accA[ni][ti] = MFMA16(wf[ni], xf[ti], accA[ni][ti]);
; #pragma unroll
;         for (int i = 0; i < 4; ++i) wf[i] = *(const bf16x8*)(Bb + 16384 + i * 2048 + sw);
; #pragma unroll
;         for (int ni = 0; ni < 4; ++ni)
; #pragma unroll
;           for (int ti = 0; ti < 4; ++ti) accB[ni][ti] = MFMA16(wf[ni], xf[ti], accB[ni][ti]);
;       }
;     };
	v_mfma_f32_16x16x32_bf16 v[146:149], v[178:181], v[220:223], v[146:149]
	ds_read_b128 v[178:181], v13 offset:16384
	s_waitcnt lgkmcnt(3)
	v_mfma_f32_16x16x32_bf16 v[142:145], v[244:247], v[182:185], v[142:145]
	v_mfma_f32_16x16x32_bf16 v[138:141], v[244:247], v[212:215], v[138:141]
	v_mfma_f32_16x16x32_bf16 v[130:133], v[244:247], v[216:219], v[130:133]
	v_mfma_f32_16x16x32_bf16 v[114:117], v[244:247], v[220:223], v[114:117]
	ds_read_b128 v[244:247], v13 offset:18432
	s_waitcnt lgkmcnt(3)
	v_mfma_f32_16x16x32_bf16 v[94:97], v[248:251], v[182:185], v[94:97]
	s_add_i32 s4, s35, 1
	s_and_b32 s4, s4, 1
	v_lshl_add_u32 v242, s4, 14, v203
	v_lshl_add_u32 v243, s4, 15, v204
	v_mfma_f32_16x16x32_bf16 v[90:93], v[248:251], v[212:215], v[90:93]
	s_waitcnt vmcnt(6)
	ds_write_b128 v242, v[118:121]
	ds_write_b128 v243, v[126:129]
	v_and_b32_e32 v129, 0xffff0000, v118
	s_waitcnt vmcnt(5)
	v_and_b32_e32 v128, 0xffff0000, v106
	v_mfma_f32_16x16x32_bf16 v[86:89], v[248:251], v[216:219], v[86:89]
	v_lshlrev_b32_e32 v127, 16, v118
	v_lshlrev_b32_e32 v126, 16, v106
	v_mul_f32_e32 v128, v128, v128
	v_mul_f32_e32 v129, v129, v129
	v_mfma_f32_16x16x32_bf16 v[82:85], v[248:251], v[220:223], v[82:85]
	v_and_b32_e32 v118, 0xffff0000, v107
	v_fma_f32 v126, v126, v126, v128
	v_fma_f32 v127, v127, v127, v129
	v_lshlrev_b32_e32 v129, 16, v119
	ds_read_b128 v[248:251], v13 offset:20480
	s_waitcnt lgkmcnt(5)
	v_mfma_f32_16x16x32_bf16 v[78:81], v[252:255], v[182:185], v[78:81]
	v_lshlrev_b32_e32 v128, 16, v107
	v_fma_f32 v126, v128, v128, v126
	v_fma_f32 v127, v129, v129, v127
	v_and_b32_e32 v119, 0xffff0000, v119
	v_mfma_f32_16x16x32_bf16 v[74:77], v[252:255], v[212:215], v[74:77]
	v_fma_f32 v118, v118, v118, v126
	v_fma_f32 v119, v119, v119, v127
	v_lshlrev_b32_e32 v127, 16, v120
	v_lshlrev_b32_e32 v126, 16, v108
	v_mfma_f32_16x16x32_bf16 v[70:73], v[252:255], v[216:219], v[70:73]
	v_fma_f32 v118, v126, v126, v118
	v_fma_f32 v119, v127, v127, v119
	v_and_b32_e32 v127, 0xffff0000, v120
	v_and_b32_e32 v126, 0xffff0000, v108
	v_mfma_f32_16x16x32_bf16 v[66:69], v[252:255], v[220:223], v[66:69]
	v_fma_f32 v118, v126, v126, v118
	v_fma_f32 v119, v127, v127, v119
	v_lshlrev_b32_e32 v126, 16, v109
	v_and_b32_e32 v120, 0xffff0000, v109
	ds_read_b128 v[252:255], v13 offset:22528
	s_waitcnt lgkmcnt(5)
	v_mfma_f32_16x16x32_bf16 v[62:65], v[178:181], v[182:185], v[62:65]
	ds_write_b128 v242, v[106:109] offset:4096
	s_waitcnt vmcnt(4)
	ds_write_b128 v243, v[122:125] offset:8192
	s_waitcnt vmcnt(3)
	ds_write_b128 v242, v[98:101] offset:8192
	v_mfma_f32_16x16x32_bf16 v[58:61], v[178:181], v[212:215], v[58:61]
	s_waitcnt vmcnt(2)
	ds_write_b128 v243, v[134:137] offset:16384
	v_and_b32_e32 v109, 0xffff0000, v98
	s_waitcnt vmcnt(1)
	v_and_b32_e32 v108, 0xffff0000, v102
	v_mfma_f32_16x16x32_bf16 v[54:57], v[178:181], v[216:219], v[54:57]
	v_lshlrev_b32_e32 v107, 16, v98
	v_lshlrev_b32_e32 v106, 16, v102
	v_mul_f32_e32 v108, v108, v108
	v_mfma_f32_16x16x32_bf16 v[50:53], v[178:181], v[220:223], v[50:53]
	v_mul_f32_e32 v109, v109, v109
	v_and_b32_e32 v98, 0xffff0000, v103
	v_fma_f32 v106, v106, v106, v108
	s_waitcnt lgkmcnt(8)
	v_mfma_f32_16x16x32_bf16 v[46:49], v[244:247], v[182:185], v[46:49]
	v_fma_f32 v107, v107, v107, v109
	v_lshlrev_b32_e32 v109, 16, v99
	v_lshlrev_b32_e32 v108, 16, v103
	v_mfma_f32_16x16x32_bf16 v[42:45], v[244:247], v[212:215], v[42:45]
	v_fma_f32 v106, v108, v108, v106
	v_fma_f32 v107, v109, v109, v107
	v_and_b32_e32 v99, 0xffff0000, v99
	v_mfma_f32_16x16x32_bf16 v[38:41], v[244:247], v[216:219], v[38:41]
	v_fma_f32 v98, v98, v98, v106
	v_fma_f32 v99, v99, v99, v107
	v_lshlrev_b32_e32 v107, 16, v100
	v_mfma_f32_16x16x32_bf16 v[34:37], v[244:247], v[220:223], v[34:37]
	v_lshlrev_b32_e32 v106, 16, v104
	v_fma_f32 v98, v106, v106, v98
	v_fma_f32 v99, v107, v107, v99
	s_waitcnt lgkmcnt(5)
	v_mfma_f32_16x16x32_bf16 v[30:33], v[248:251], v[182:185], v[30:33]
	v_and_b32_e32 v107, 0xffff0000, v100
	v_and_b32_e32 v106, 0xffff0000, v104
	v_lshlrev_b32_e32 v127, 16, v121
	v_mfma_f32_16x16x32_bf16 v[26:29], v[248:251], v[212:215], v[26:29]
	v_fma_f32 v98, v106, v106, v98
	v_fma_f32 v99, v107, v107, v99
	v_lshlrev_b32_e32 v107, 16, v101
	v_mfma_f32_16x16x32_bf16 v[22:25], v[248:251], v[216:219], v[22:25]
	v_lshlrev_b32_e32 v106, 16, v105
	v_fma_f32 v118, v126, v126, v118
	v_fma_f32 v119, v127, v127, v119
	v_mfma_f32_16x16x32_bf16 v[18:21], v[248:251], v[220:223], v[18:21]
	v_and_b32_e32 v121, 0xffff0000, v121
	v_fma_f32 v98, v106, v106, v98
	v_fma_f32 v99, v107, v107, v99
	s_waitcnt lgkmcnt(4)
	v_mfma_f32_16x16x32_bf16 v[14:17], v[252:255], v[182:185], v[14:17]
	v_and_b32_e32 v101, 0xffff0000, v101
	v_and_b32_e32 v100, 0xffff0000, v105
	v_fma_f32 v118, v120, v120, v118
	v_mfma_f32_16x16x32_bf16 v[8:11], v[252:255], v[212:215], v[8:11]
	v_fma_f32 v119, v121, v121, v119
	v_fma_f32 v98, v100, v100, v98
	v_fma_f32 v99, v101, v101, v99
	v_mfma_f32_16x16x32_bf16 v[4:7], v[252:255], v[216:219], v[4:7]
	v_add_f32_e32 v176, v176, v118
	v_add_f32_e32 v177, v177, v119
	v_add_f32_e32 v170, v170, v98
	v_mfma_f32_16x16x32_bf16 v[0:3], v[252:255], v[220:223], v[0:3]
	v_add_f32_e32 v171, v171, v99
	ds_write_b128 v242, v[102:105] offset:12288
	s_waitcnt vmcnt(0)
	ds_write_b128 v243, v[110:113] offset:24576
	s_cmp_lg_u32 s6, 16
	s_cbranch_scc1 .LBB0_1094
	ds_read2_b32 v[180:181], v210 offset1:16
	ds_read2_b32 v[178:179], v210 offset0:32 offset1:48
	s_cmpk_gt_i32 s62, 0x4ff
	s_mov_b64 s[4:5], -1
	s_cbranch_scc0 .LBB0_1047
	s_add_i32 s7, s62, 0xfffffb00
	s_movk_i32 s4, 0x4000
	s_cbranch_execz .LBB0_1048

; __device__ __forceinline__ void rem_tile(int pos, int& mt, int& nt) { if (pos < 65) { mt = pos; nt = 40; } else { mt = 64; nt = pos - 65; } }
;     ...
;     auto issue = [&](u32x4 (&ra)[4], u32x4 (&rb)[2], u32x4& rx) {
;       const int idc = l_id < last_id ? l_id : last_id;
;       int mt, nt; if (TMAP == 1) rem_tile(idc, mt, nt); else tile_of(idc, ntn, mt, nt);
;       const bf16_t* A = (l_kt < ktsplit) ? A0 : A1;
;       const int kk = (l_kt < ktsplit) ? l_kt : l_kt - ktsplit;
;       const int arow = mt * 2 * BMH + hh * BMH + srow;
;     ...
;     auto compute = [&](int buf) {
;       const unsigned char* Ab = As + buf * ASTG + (wn * 64 + lr) * 128;
;       const unsigned char* Ax = Ax0 + buf * 128;
;       const unsigned char* Bb = Bs + buf * 16384 + (wm * 64 + lr) * 128;
; #pragma unroll
;       for (int ks = 0; ks < 2; ++ks) {
;         if (TI == 5 && ks == 1) __builtin_amdgcn_sched_barrier(0);
;         const int sw = ((ks * 4 + lq) ^ (lr & 7)) << 4;
;         bf16x8 wf[4], xf[TI];
; #pragma unroll
;         for (int i = 0; i < 4; ++i) {
;           wf[i] = *(const bf16x8*)(Bb + i * 2048 + sw);
;           xf[i] = *(const bf16x8*)(Ab + i * 2048 + sw);
;         }
;         if (TI == 5) xf[TI - 1] = *(const bf16x8*)(Ax + ((ks * 4 + lq) << 4));
.LBB0_1780:
	v_add_u32_e32 v13, v180, v181
	ds_read_b128 v[148:151], v13 offset:32768
	v_add_u32_e32 v15, v179, v181
	ds_read_b128 v[56:59], v15
	ds_read_b128 v[152:155], v13 offset:34816
	s_waitcnt vmcnt(8)
	ds_read_b128 v[64:67], v15 offset:2048
	ds_read_b128 v[160:163], v15 offset:4096
	ds_read_b128 v[204:207], v15 offset:6144
	s_min_i32 s10, s7, s13
	s_cmpk_gt_i32 s10, 0x1ff
	s_mov_b64 s[4:5], -1
	s_cbranch_scc0 .LBB0_1782
	s_add_i32 s9, s10, 0xfffffe00
	s_mov_b64 s[4:5], 0

; #define MFMA16(a, b, c) __builtin_amdgcn_mfma_f32_16x16x32_bf16((a), (b), (c), 0, 0, 0)
;     ...
;     auto issue = [&](u32x4 (&ra)[4], u32x4 (&rb)[2], u32x4& rx) {
;       const int idc = l_id < last_id ? l_id : last_id;
;       int mt, nt; if (TMAP == 1) rem_tile(idc, mt, nt); else tile_of(idc, ntn, mt, nt);
;       const bf16_t* A = (l_kt < ktsplit) ? A0 : A1;
;       const int kk = (l_kt < ktsplit) ? l_kt : l_kt - ktsplit;
;       const int arow = mt * 2 * BMH + hh * BMH + srow;
;       const bf16_t* akb = A + kk * kstride + (tid & 7) * 8;
;       const bf16_t* wp = W + (size_t)(nt * 128 + wrow) * K + l_kt * 64 + (tid5 & 7) * 8;
; #pragma unroll
;       for (int i = 0; i < 4; ++i) {
;         int r = arow + 32 * i; r = r < M_ ? r : M_ - 1;
;         ra[i] = *(const u32x4*)(akb + (size_t)r * lda);
;       }
; #pragma unroll
;       for (int i = 0; i < 2; ++i) rb[i] = *(const u32x4*)(wp + (size_t)i * 64 * K);
;       if (TI == 5) rx = *(const u32x4*)(akb + (size_t)(arow - srow + 128) * lda);
;       if (++l_kt == nk) { l_kt = 0; l_id += G; }
;     };
;     ...
;     auto compute = [&](int buf) {
;       const unsigned char* Ab = As + buf * ASTG + (wn * 64 + lr) * 128;
;       const unsigned char* Ax = Ax0 + buf * 128;
;       const unsigned char* Bb = Bs + buf * 16384 + (wm * 64 + lr) * 128;
; #pragma unroll
;       for (int ks = 0; ks < 2; ++ks) {
;         if (TI == 5 && ks == 1) __builtin_amdgcn_sched_barrier(0);
;         const int sw = ((ks * 4 + lq) ^ (lr & 7)) << 4;
;         bf16x8 wf[4], xf[TI];
; #pragma unroll
;         for (int i = 0; i < 4; ++i) {
;           wf[i] = *(const bf16x8*)(Bb + i * 2048 + sw);
;           xf[i] = *(const bf16x8*)(Ab + i * 2048 + sw);
;         }
;         if (TI == 5) xf[TI - 1] = *(const bf16x8*)(Ax + ((ks * 4 + lq) << 4));
; #pragma unroll
;         for (int ni = 0; ni < 4; ++ni)
; #pragma unroll
;           for (int ti = 0; ti < 4; ++ti) acc[ni][ti] = MFMA16(wf[ni], xf[ti], acc[ni][ti]);
;         if (TI == 5) {
;           if (wn == 0) { acc[0][TI - 1] = MFMA16(wf[0], xf[TI - 1], acc[0][TI - 1]); acc[1][TI - 1] = MFMA16(wf[1], xf[TI - 1], acc[1][TI - 1]); }
;           else { acc[2][TI - 1] = MFMA16(wf[2], xf[TI - 1], acc[2][TI - 1]); acc[3][TI - 1] = MFMA16(wf[3], xf[TI - 1], acc[3][TI - 1]); }
;         }
;       }
;     };
.LBB0_1784:
	s_cmp_lt_i32 s6, 16
	s_cselect_b32 s5, 0, -16
	s_cselect_b32 s10, s47, s55
	s_cselect_b32 s11, s46, s54
	s_add_i32 s5, s5, s6
	v_add_u32_e32 v14, s4, v176
	s_lshl_b32 s4, s5, 6
	s_ashr_i32 s5, s4, 31
	s_lshl_b64 s[4:5], s[4:5], 1
	s_add_u32 s4, s11, s4
	v_min_i32_e32 v42, 0x405f, v14
	s_addc_u32 s5, s10, s5
	v_mov_b32_e32 v169, v12
	v_ashrrev_i32_e32 v43, 31, v42
	v_lshl_add_u64 v[208:209], s[4:5], 0, v[168:169]
	v_min_i32_e32 v40, 0x407f, v14
	v_lshlrev_b64 v[42:43], 11, v[42:43]
	v_ashrrev_i32_e32 v41, 31, v40
	v_lshl_add_u64 v[42:43], v[208:209], 0, v[42:43]
	v_lshlrev_b64 v[40:41], 11, v[40:41]
	v_add_co_u32_e32 v44, vcc, s82, v42
	v_lshl_add_u64 v[40:41], v[208:209], 0, v[40:41]
	s_nop 0
	v_addc_co_u32_e32 v45, vcc, 0, v43, vcc
	s_waitcnt lgkmcnt(1)
	v_mfma_f32_16x16x32_bf16 v[140:143], v[148:151], v[160:163], v[128:131]
	global_load_dwordx4 v[40:43], v[40:41], off
	s_nop 0
	global_load_dwordx4 v[44:47], v[44:45], off
	ds_read_b128 v[128:131], v13 offset:36864
	ds_read_b128 v[156:159], v13 offset:38912
	v_min_i32_e32 v48, 0x403f, v14
	v_ashrrev_i32_e32 v49, 31, v48
	v_lshl_add_u32 v60, s9, 7, v174
	v_lshlrev_b64 v[48:49], 11, v[48:49]
	v_min_i32_e32 v50, 0x401f, v14
	v_ashrrev_i32_e32 v61, 31, v60
	v_lshl_add_u64 v[48:49], v[208:209], 0, v[48:49]
	v_ashrrev_i32_e32 v51, 31, v50
	s_lshl_b32 s4, s6, 6
	v_add_co_u32_e32 v48, vcc, s2, v48
	v_lshlrev_b64 v[50:51], 11, v[50:51]
	v_lshlrev_b64 v[60:61], 12, v[60:61]
	s_ashr_i32 s5, s4, 31
	v_addc_co_u32_e32 v49, vcc, 0, v49, vcc
	v_lshl_add_u64 v[50:51], v[208:209], 0, v[50:51]
	s_mov_b32 s3, 0x30000
	v_lshl_add_u64 v[60:61], s[48:49], 0, v[60:61]
	v_sub_u32_e32 v14, v14, v173
	s_waitcnt lgkmcnt(1)
	v_mfma_f32_16x16x32_bf16 v[144:147], v[128:131], v[56:59], v[100:103]
	v_add_co_u32_e32 v52, vcc, s3, v50
	v_lshl_add_u64 v[60:61], s[4:5], 1, v[60:61]
	v_mov_b32_e32 v171, v12
	v_add_u32_e32 v100, 0x80, v14
	v_addc_co_u32_e32 v53, vcc, 0, v51, vcc
	v_lshl_add_u64 v[60:61], v[60:61], 0, v[170:171]
	s_mov_b32 s3, 0x40000
	v_ashrrev_i32_e32 v101, 31, v100
	v_mfma_f32_16x16x32_bf16 v[132:135], v[148:151], v[64:67], v[132:135]
	v_add_co_u32_e32 v62, vcc, s3, v60
	global_load_dwordx4 v[48:51], v[48:49], off
	s_nop 0
	global_load_dwordx4 v[52:55], v[52:53], off
	v_mfma_f32_16x16x32_bf16 v[116:119], v[152:155], v[64:67], v[116:119]
	v_addc_co_u32_e32 v63, vcc, 0, v61, vcc
	v_mfma_f32_16x16x32_bf16 v[96:99], v[128:131], v[64:67], v[96:99]
	s_waitcnt lgkmcnt(0)
	v_mfma_f32_16x16x32_bf16 v[76:79], v[156:159], v[64:67], v[76:79]
	v_lshlrev_b64 v[64:65], 11, v[100:101]
	v_lshl_add_u64 v[64:65], v[208:209], 0, v[64:65]
	v_mfma_f32_16x16x32_bf16 v[136:139], v[148:151], v[56:59], v[136:139]
	v_mfma_f32_16x16x32_bf16 v[120:123], v[152:155], v[56:59], v[120:123]
	v_mfma_f32_16x16x32_bf16 v[80:83], v[156:159], v[56:59], v[80:83]
	global_load_dwordx4 v[56:59], v[60:61], off
	s_nop 0
	global_load_dwordx4 v[60:63], v[62:63], off
	ds_read_b128 v[100:103], v185
	global_load_dwordx4 v[64:67], v[64:65], off
	s_sub_u32 s101, s8, 14
	s_lshr_b32 s101, s101, 1
	s_lshl_b32 s101, s101, 14
	s_add_u32 s101, s101, s100
	v_add_u32_e32 v250, s101, v251
	s_sub_u32 s101, s8, 14
	s_cmp_le_u32 s101, 14
	s_cselect_b32 s101, -1, 0
	v_and_b32_e32 v250, s101, v250
	global_load_dword v249, v250, s[44:45]
	v_mfma_f32_16x16x32_bf16 v[124:127], v[148:151], v[204:207], v[124:127]
	v_mfma_f32_16x16x32_bf16 v[112:115], v[152:155], v[160:163], v[112:115]
	v_mfma_f32_16x16x32_bf16 v[104:107], v[152:155], v[204:207], v[104:107]
	v_mfma_f32_16x16x32_bf16 v[92:95], v[128:131], v[160:163], v[92:95]
	v_mfma_f32_16x16x32_bf16 v[84:87], v[128:131], v[204:207], v[84:87]
	v_mfma_f32_16x16x32_bf16 v[72:75], v[156:159], v[160:163], v[72:75]
	v_mfma_f32_16x16x32_bf16 v[68:71], v[156:159], v[204:207], v[68:71]
	s_and_saveexec_b64 s[4:5], s[40:41]
	s_xor_b64 s[4:5], exec, s[4:5]
	s_cbranch_execz .LBB0_1786
	s_waitcnt lgkmcnt(0)
	v_mfma_f32_16x16x32_bf16 v[36:39], v[128:131], v[100:103], v[36:39]
	v_mfma_f32_16x16x32_bf16 v[8:11], v[156:159], v[100:103], v[8:11]

; __device__ __forceinline__ void rem_tile(int pos, int& mt, int& nt) { if (pos < 65) { mt = pos; nt = 40; } else { mt = 64; nt = pos - 65; } }
;     ...
;     auto issue = [&](u32x4 (&ra)[4], u32x4 (&rb)[2], u32x4& rx) {
;       const int idc = l_id < last_id ? l_id : last_id;
;       int mt, nt; if (TMAP == 1) rem_tile(idc, mt, nt); else tile_of(idc, ntn, mt, nt);
;       const bf16_t* A = (l_kt < ktsplit) ? A0 : A1;
;       const int kk = (l_kt < ktsplit) ? l_kt : l_kt - ktsplit;
;       const int arow = mt * 2 * BMH + hh * BMH + srow;
;     ...
; #pragma unroll 1
;     for (int s = 0; s < S; s += 2) {
;       issue(ra0, rb0, rx0);
;       compute(0);
;       store(ra1, rb1, rx1, 1);
;       __syncthreads();
;       issue(ra1, rb1, rx1);
.LBB0_1794:
	s_or_b64 exec, exec, s[4:5]
	s_add_i32 s10, s6, 1
	s_cmp_eq_u32 s10, 32
	s_cselect_b64 s[4:5], -1, 0
	s_and_b64 s[34:35], s[4:5], exec
	s_load_dwordx2 s[34:35], s[0:1], 0x110
	s_waitcnt lgkmcnt(0)
	s_barrier
	ds_read_b128 v[148:151], v13 offset:49152
	ds_read_b128 v[24:27], v15 offset:16384
	ds_read_b128 v[152:155], v13 offset:51200
	s_waitcnt vmcnt(8)
	ds_read_b128 v[32:35], v15 offset:18432
	ds_read_b128 v[160:163], v15 offset:20480
	ds_read_b128 v[204:207], v15 offset:22528
	s_cselect_b32 s57, s34, 0
	s_add_i32 s57, s57, s7
	s_min_i32 s11, s57, s13
	s_cmpk_gt_i32 s11, 0x1ff
	s_mov_b64 s[6:7], -1
	s_cbranch_scc0 .LBB0_1796
	s_add_i32 s9, s11, 0xfffffe00
	s_mov_b64 s[6:7], 0

; #define MFMA16(a, b, c) __builtin_amdgcn_mfma_f32_16x16x32_bf16((a), (b), (c), 0, 0, 0)
;     ...
;     auto issue = [&](u32x4 (&ra)[4], u32x4 (&rb)[2], u32x4& rx) {
;       const int idc = l_id < last_id ? l_id : last_id;
;       int mt, nt; if (TMAP == 1) rem_tile(idc, mt, nt); else tile_of(idc, ntn, mt, nt);
;       const bf16_t* A = (l_kt < ktsplit) ? A0 : A1;
;       const int kk = (l_kt < ktsplit) ? l_kt : l_kt - ktsplit;
;       const int arow = mt * 2 * BMH + hh * BMH + srow;
;       const bf16_t* akb = A + kk * kstride + (tid & 7) * 8;
;       const bf16_t* wp = W + (size_t)(nt * 128 + wrow) * K + l_kt * 64 + (tid5 & 7) * 8;
; #pragma unroll
;       for (int i = 0; i < 4; ++i) {
;         int r = arow + 32 * i; r = r < M_ ? r : M_ - 1;
;         ra[i] = *(const u32x4*)(akb + (size_t)r * lda);
;       }
; #pragma unroll
;       for (int i = 0; i < 2; ++i) rb[i] = *(const u32x4*)(wp + (size_t)i * 64 * K);
;       if (TI == 5) rx = *(const u32x4*)(akb + (size_t)(arow - srow + 128) * lda);
;       if (++l_kt == nk) { l_kt = 0; l_id += G; }
;     };
;     ...
;     auto compute = [&](int buf) {
;       const unsigned char* Ab = As + buf * ASTG + (wn * 64 + lr) * 128;
;       const unsigned char* Ax = Ax0 + buf * 128;
;       const unsigned char* Bb = Bs + buf * 16384 + (wm * 64 + lr) * 128;
; #pragma unroll
;       for (int ks = 0; ks < 2; ++ks) {
;         if (TI == 5 && ks == 1) __builtin_amdgcn_sched_barrier(0);
;         const int sw = ((ks * 4 + lq) ^ (lr & 7)) << 4;
;         bf16x8 wf[4], xf[TI];
; #pragma unroll
;         for (int i = 0; i < 4; ++i) {
;           wf[i] = *(const bf16x8*)(Bb + i * 2048 + sw);
;           xf[i] = *(const bf16x8*)(Ab + i * 2048 + sw);
;         }
;         if (TI == 5) xf[TI - 1] = *(const bf16x8*)(Ax + ((ks * 4 + lq) << 4));
; #pragma unroll
;         for (int ni = 0; ni < 4; ++ni)
; #pragma unroll
;           for (int ti = 0; ti < 4; ++ti) acc[ni][ti] = MFMA16(wf[ni], xf[ti], acc[ni][ti]);
;         if (TI == 5) {
;           if (wn == 0) { acc[0][TI - 1] = MFMA16(wf[0], xf[TI - 1], acc[0][TI - 1]); acc[1][TI - 1] = MFMA16(wf[1], xf[TI - 1], acc[1][TI - 1]); }
;           else { acc[2][TI - 1] = MFMA16(wf[2], xf[TI - 1], acc[2][TI - 1]); acc[3][TI - 1] = MFMA16(wf[3], xf[TI - 1], acc[3][TI - 1]); }
;         }
;       }
;     };
.LBB0_1798:
	s_and_b64 s[4:5], s[4:5], exec
	s_cselect_b32 s58, 0, s10
	s_cmp_lt_i32 s58, 16
	s_cselect_b32 s4, 0, -16
	s_cselect_b32 s7, s47, s55
	s_cselect_b32 s10, s46, s54
	s_add_i32 s4, s4, s58
	s_lshl_b32 s4, s4, 6
	s_ashr_i32 s5, s4, 31
	v_add_u32_e32 v210, s6, v176
	s_lshl_b64 s[4:5], s[4:5], 1
	s_add_u32 s4, s10, s4
	v_min_i32_e32 v2, 0x405f, v210
	s_addc_u32 s5, s7, s5
	v_mov_b32_e32 v169, v12
	v_ashrrev_i32_e32 v3, 31, v2
	v_lshl_add_u64 v[208:209], s[4:5], 0, v[168:169]
	v_min_i32_e32 v0, 0x407f, v210
	v_lshlrev_b64 v[2:3], 11, v[2:3]
	v_ashrrev_i32_e32 v1, 31, v0
	v_lshl_add_u64 v[2:3], v[208:209], 0, v[2:3]
	v_lshlrev_b64 v[0:1], 11, v[0:1]
	v_add_co_u32_e32 v4, vcc, s82, v2
	v_lshl_add_u64 v[0:1], v[208:209], 0, v[0:1]
	s_nop 0
	v_addc_co_u32_e32 v5, vcc, 0, v3, vcc
	s_waitcnt lgkmcnt(1)
	v_mfma_f32_16x16x32_bf16 v[140:143], v[148:151], v[160:163], v[132:135]
	global_load_dwordx4 v[0:3], v[0:1], off
	s_nop 0
	global_load_dwordx4 v[4:7], v[4:5], off
	ds_read_b128 v[132:135], v13 offset:53248
	ds_read_b128 v[156:159], v13 offset:55296
	v_min_i32_e32 v16, 0x403f, v210
	v_ashrrev_i32_e32 v17, 31, v16
	v_lshl_add_u32 v28, s9, 7, v174
	v_lshlrev_b64 v[16:17], 11, v[16:17]
	v_min_i32_e32 v18, 0x401f, v210
	v_ashrrev_i32_e32 v29, 31, v28
	v_lshl_add_u64 v[16:17], v[208:209], 0, v[16:17]
	v_ashrrev_i32_e32 v19, 31, v18
	s_lshl_b32 s4, s58, 6
	v_add_co_u32_e32 v16, vcc, s2, v16
	v_lshlrev_b64 v[18:19], 11, v[18:19]
	v_lshlrev_b64 v[28:29], 12, v[28:29]
	s_ashr_i32 s5, s4, 31
	v_addc_co_u32_e32 v17, vcc, 0, v17, vcc
	v_lshl_add_u64 v[18:19], v[208:209], 0, v[18:19]
	s_mov_b32 s3, 0x30000
	v_lshl_add_u64 v[28:29], s[48:49], 0, v[28:29]
	v_sub_u32_e32 v13, v210, v173
	s_waitcnt lgkmcnt(1)
	v_mfma_f32_16x16x32_bf16 v[144:147], v[132:135], v[24:27], v[104:107]
	v_add_co_u32_e32 v20, vcc, s3, v18
	v_lshl_add_u64 v[28:29], s[4:5], 1, v[28:29]
	v_mov_b32_e32 v171, v12
	v_add_u32_e32 v104, 0x80, v13
	v_addc_co_u32_e32 v21, vcc, 0, v19, vcc
	v_lshl_add_u64 v[28:29], v[28:29], 0, v[170:171]
	s_mov_b32 s3, 0x40000
	v_ashrrev_i32_e32 v105, 31, v104
	v_mfma_f32_16x16x32_bf16 v[128:131], v[148:151], v[32:35], v[128:131]
	v_add_co_u32_e32 v30, vcc, s3, v28
	global_load_dwordx4 v[16:19], v[16:17], off
	s_nop 0
	global_load_dwordx4 v[20:23], v[20:21], off
	v_mfma_f32_16x16x32_bf16 v[116:119], v[152:155], v[32:35], v[116:119]
	v_addc_co_u32_e32 v31, vcc, 0, v29, vcc
	v_mfma_f32_16x16x32_bf16 v[96:99], v[132:135], v[32:35], v[96:99]
	s_waitcnt lgkmcnt(0)
	v_mfma_f32_16x16x32_bf16 v[76:79], v[156:159], v[32:35], v[76:79]
	v_lshlrev_b64 v[32:33], 11, v[104:105]
	v_lshl_add_u64 v[32:33], v[208:209], 0, v[32:33]
	v_mfma_f32_16x16x32_bf16 v[136:139], v[148:151], v[24:27], v[136:139]
	v_mfma_f32_16x16x32_bf16 v[120:123], v[152:155], v[24:27], v[120:123]
	v_mfma_f32_16x16x32_bf16 v[80:83], v[156:159], v[24:27], v[80:83]
	global_load_dwordx4 v[24:27], v[28:29], off
	s_nop 0
	global_load_dwordx4 v[28:31], v[30:31], off
	ds_read_b128 v[104:107], v185 offset:128
	global_load_dwordx4 v[32:35], v[32:33], off
	s_sub_u32 s101, s8, 14
	s_lshr_b32 s101, s101, 1
	s_lshl_b32 s101, s101, 14
	s_add_u32 s101, s101, s100
	v_add_u32_e32 v250, s101, v251
	s_sub_u32 s101, s8, 14
	s_cmp_le_u32 s101, 14
	s_cselect_b32 s101, -1, 0
	v_and_b32_e32 v250, s101, v250
	global_load_dword v249, v250, s[50:51]
	v_mfma_f32_16x16x32_bf16 v[124:127], v[148:151], v[204:207], v[124:127]
	v_mfma_f32_16x16x32_bf16 v[112:115], v[152:155], v[160:163], v[112:115]
	v_mfma_f32_16x16x32_bf16 v[100:103], v[152:155], v[204:207], v[100:103]
	v_mfma_f32_16x16x32_bf16 v[92:95], v[132:135], v[160:163], v[92:95]
	v_mfma_f32_16x16x32_bf16 v[84:87], v[132:135], v[204:207], v[84:87]
	v_mfma_f32_16x16x32_bf16 v[72:75], v[156:159], v[160:163], v[72:75]
	v_mfma_f32_16x16x32_bf16 v[68:71], v[156:159], v[204:207], v[68:71]
	s_and_saveexec_b64 s[4:5], s[40:41]
	s_xor_b64 s[4:5], exec, s[4:5]
	s_cbranch_execz .LBB0_1800
	s_waitcnt lgkmcnt(0)
	v_mfma_f32_16x16x32_bf16 v[36:39], v[132:135], v[104:107], v[36:39]
	v_mfma_f32_16x16x32_bf16 v[8:11], v[156:159], v[104:107], v[8:11]
